# attention K-fragment LDS addresses kept in 8 persistent VGPRs toggled by xor once per iteration (16 v_add_u32 -> 8 v_xor per iteration, slot folded into ds_read offset)
# baseline (speedup 1.0000x reference)
; __device__ __forceinline__ void attn_item(const bf16_t* __restrict__ Qb, const bf16_t* __restrict__ Kh, const bf16_t* __restrict__ Vh, const bf16_t* __restrict__ Zb, ...
;     ...
;   const bf16_t* Qw = Qb + (long)(wid * QBLK + r32) * LDQ + hi * 8;
;   float qn2 = 0.f;
;   {
;     u32x4 qw[8];
; #pragma unroll
;     for (int d0 = 0; d0 < 8; ++d0) qw[d0] = *reinterpret_cast<const u32x4*>(Qw + d0 * 16);
;     float ss = 0.f;
; #pragma unroll
;     for (int d0 = 0; d0 < 8; ++d0) { const float a0 = bflo(qw[d0].x), a1 = bfhi(qw[d0].x), a2 = bflo(qw[d0].y), a3 = bfhi(qw[d0].y), a4 = bflo(qw[d0].z), a5 = bfhi(qw[d0].z), a6 = bflo(qw[d0].w), a7 = bfhi(qw[d0].w);
;       ss += (a0 * a0 + a1 * a1) + (a2 * a2 + a3 * a3) + (a4 * a4 + a5 * a5) + (a6 * a6 + a7 * a7); }
;     { auto rr = __builtin_amdgcn_permlane32_swap(__float_as_uint(ss), __float_as_uint(ss), false, false); ss = __uint_as_float(rr[0]) + __uint_as_float(rr[1]); }
;     const float rstd = __builtin_amdgcn_rsqf(ss * (1.0f / 128.0f) + NORM_EPS) * (SCALE * 1.4426950408889634f);
;     const int hq = lane_id_asm() >> 5;
;     const int spos = qpos0 + wid * QBLK + r32; const float prow = (float)(spos >> 6), pcol = (float)(spos & 63);
; #pragma unroll
;     for (int bb = 0; bb < 4; ++bb) { const int d1 = (bb & 1) + 4 * (bb >> 1), d2 = d1 + 2;
;       const float pos = (bb < 2) ? prow : pcol; const float* g1p = qg + d1 * 16 + hq * 8; const float* g2p = qg + d2 * 16 + hq * 8;
;       const f32x4 g1a = *(const f32x4*)g1p, g1b = *(const f32x4*)(g1p + 4), g2a = *(const f32x4*)g2p, g2b = *(const f32x4*)(g2p + 4);
;       float o1[8], o2[8];
; #pragma unroll
;       for (int e = 0; e < 8; ++e) { const unsigned w1 = (e < 2) ? qw[d1].x : (e < 4) ? qw[d1].y : (e < 6) ? qw[d1].z : qw[d1].w, w2 = (e < 2) ? qw[d2].x : (e < 4) ? qw[d2].y : (e < 6) ? qw[d2].z : qw[d2].w;
;         const float x1 = (e & 1) ? bfhi(w1) : bflo(w1), x2 = (e & 1) ? bfhi(w2) : bflo(w2); const float ga = (e < 4) ? g1a[e & 3] : g1b[e & 3], gb = (e < 4) ? g2a[e & 3] : g2b[e & 3];
;         const int fi = (d1 & 1) * 16 + hq * 8 + e; float rev = pos * (__builtin_amdgcn_exp2f(-(float)fi * (13.287712379549449f / 32.0f)) * 0.15915494309189535f); rev -= floorf(rev);
;         const float sn = sin_rev(rev), cs = cos_rev(rev), y1 = x1 * rstd * ga, y2 = x2 * rstd * gb; o1[e] = y1 * cs - y2 * sn; o2[e] = y2 * cs + y1 * sn; }
.LBB0_452:
	s_lshl_b32 s0, s70, 5
	s_and_b32 s0, s0, 32
	s_bfe_u32 s7, s70, 0x50003
	s_or_b32 s7, s0, s7
	s_lshl_b32 s0, s70, 12
	s_and_b32 s0, s0, 0x4000
	s_lshl_b32 s7, s7, 8
	s_bfe_u32 s1, s70, 0x10001
	s_or_b32 s71, s7, s0
	s_bfe_u32 s6, s54, 0x1000e
	s_lshl_b32 s8, s1, 8
	s_mul_i32 s9, s71, 0x2080
	s_add_u32 s9, s42, s9
	s_addc_u32 s36, s43, 0
	s_ashr_i32 s24, s70, 1
	s_lshl_b32 s1, s1, 9
	s_and_b32 s24, s24, 0xffffff80
	s_add_i32 s24, s1, s24
	s_ashr_i32 s25, s24, 31
	s_lshl_b64 s[26:27], s[24:25], 1
	s_add_u32 s24, s9, s26
	v_mbcnt_lo_u32_b32 v0, -1, 0
	v_mbcnt_hi_u32_b32 v0, -1, v0
	s_addc_u32 s25, s36, s27
	v_add_u32_e32 v186, s33, v0
	v_mov_b64_e32 v[2:3], s[24:25]
	v_ashrrev_i32_e32 v0, 1, v186
	v_and_b32_e32 v4, 0xffffffe0, v0
	v_bfi_b32 v0, s57, v0, v186
	v_lshrrev_b32_e32 v188, 1, v186
	v_mad_i64_i32 v[2:3], s[36:37], v0, s51, v[2:3]
	v_and_b32_e32 v212, 16, v188
	v_mov_b32_e32 v213, v1
	v_mov_b32_e32 v16, v1
	v_mov_b32_e32 v17, v1
	v_mov_b32_e32 v18, v1
	v_mov_b32_e32 v19, v1
	v_mov_b32_e32 v20, v1
	v_mov_b32_e32 v21, v1
	v_mov_b32_e32 v22, v1
	v_mov_b32_e32 v23, v1
	v_mov_b32_e32 v24, v1
	v_mov_b32_e32 v25, v1
	v_mov_b32_e32 v26, v1
	v_mov_b32_e32 v27, v1
	v_mov_b32_e32 v28, v1
	v_mov_b32_e32 v29, v1
	v_mov_b32_e32 v30, v1
	v_mov_b32_e32 v31, v1
	v_lshl_add_u64 v[2:3], v[2:3], 0, v[212:213]
	global_load_dwordx4 v[36:39], v[2:3], off
	global_load_dwordx4 v[44:47], v[2:3], off offset:32
	global_load_dwordx4 v[40:43], v[2:3], off offset:64
	global_load_dwordx4 v[48:51], v[2:3], off offset:96
	global_load_dwordx4 v[52:55], v[2:3], off offset:128
	global_load_dwordx4 v[60:63], v[2:3], off offset:160
	global_load_dwordx4 v[56:59], v[2:3], off offset:192
	global_load_dwordx4 v[64:67], v[2:3], off offset:224
	v_mbcnt_lo_u32_b32 v0, -1, 0
	v_mbcnt_hi_u32_b32 v0, -1, v0
	v_and_b32_e32 v187, 31, v186
	v_ashrrev_i32_e32 v0, 2, v0
	v_and_b32_e32 v78, -8, v0
	v_or_b32_e32 v69, 1, v78
	v_cvt_f32_i32_e32 v69, v69
	v_cvt_f32_i32_e32 v6, v78
	v_or_b32_e32 v2, s7, v187
	s_waitcnt vmcnt(22)
	v_add_u32_e32 v136, v2, v4
	v_mul_f32_e32 v69, 0xbed49a78, v69
	v_exp_f32_e32 v69, v69
	v_mul_f32_e32 v6, 0xbed49a78, v6
	v_ashrrev_i32_e32 v2, 6, v136
	v_exp_f32_e32 v68, v6
	v_mul_f32_e32 v138, 0.15915494, v69
	v_or_b32_e32 v69, 2, v78
	s_waitcnt vmcnt(20)
	v_cvt_f32_i32_e32 v145, v2
	v_cvt_f32_i32_e32 v69, v69
	v_ashrrev_i32_e32 v79, 31, v78
	v_lshl_add_u64 v[14:15], v[78:79], 2, s[18:19]
	global_load_dwordx4 v[10:13], v[14:15], off
	global_load_dwordx4 v[2:5], v[14:15], off offset:16
	global_load_dwordx4 v[32:35], v[14:15], off offset:128
	global_load_dwordx4 v[6:9], v[14:15], off offset:144
	v_mul_f32_e32 v137, 0.15915494, v68
	v_mul_f32_e32 v68, v137, v145
	v_mul_f32_e32 v69, 0xbed49a78, v69
	v_floor_f32_e32 v68, v68
	v_exp_f32_e32 v69, v69
	v_fma_f32 v68, v137, v145, -v68
	v_sin_f32_e32 v104, v68
	v_cos_f32_e32 v105, v68
	v_mul_f32_e32 v68, v138, v145
	v_floor_f32_e32 v68, v68
	v_fma_f32 v68, v138, v145, -v68
	v_mul_f32_e32 v139, 0.15915494, v69
	v_sin_f32_e32 v83, v68
	v_cos_f32_e32 v82, v68
	v_or_b32_e32 v68, 3, v78
	v_mul_f32_e32 v69, v139, v145
	v_cvt_f32_i32_e32 v68, v68
	v_floor_f32_e32 v69, v69
	v_fma_f32 v69, v139, v145, -v69
	v_sin_f32_e32 v106, v69
	v_cos_f32_e32 v107, v69
	v_or_b32_e32 v69, 4, v78
	v_cvt_f32_i32_e32 v69, v69
	v_mul_f32_e32 v68, 0xbed49a78, v68
	v_exp_f32_e32 v68, v68
	v_or_b32_e32 v0, 7, v0
	v_mul_f32_e32 v69, 0xbed49a78, v69
	v_exp_f32_e32 v69, v69
	v_mul_f32_e32 v140, 0.15915494, v68
	v_mul_f32_e32 v68, v140, v145
	v_floor_f32_e32 v68, v68
	v_fma_f32 v68, v140, v145, -v68
	v_mul_f32_e32 v141, 0.15915494, v69
	v_sin_f32_e32 v97, v68
	v_cos_f32_e32 v96, v68
	v_or_b32_e32 v68, 5, v78
	v_mul_f32_e32 v69, v141, v145
	v_cvt_f32_i32_e32 v68, v68
	v_floor_f32_e32 v69, v69
	v_fma_f32 v69, v141, v145, -v69
	v_sin_f32_e32 v108, v69
	v_cos_f32_e32 v109, v69
	v_or_b32_e32 v69, 6, v78
	v_cvt_f32_i32_e32 v69, v69
	v_mul_f32_e32 v68, 0xbed49a78, v68
	v_exp_f32_e32 v68, v68
	v_cvt_f32_i32_e32 v0, v0
	v_mul_f32_e32 v69, 0xbed49a78, v69
	v_exp_f32_e32 v69, v69
	v_mul_f32_e32 v142, 0.15915494, v68
	v_mul_f32_e32 v68, v142, v145
	v_floor_f32_e32 v68, v68
	v_fma_f32 v68, v142, v145, -v68
	v_mul_f32_e32 v143, 0.15915494, v69
	v_mul_f32_e32 v0, 0xbed49a78, v0
	v_sin_f32_e32 v101, v68
	v_cos_f32_e32 v100, v68
	v_mul_f32_e32 v68, v143, v145
	v_exp_f32_e32 v0, v0
	v_floor_f32_e32 v68, v68
	v_fma_f32 v68, v143, v145, -v68
	v_sin_f32_e32 v110, v68
	v_cos_f32_e32 v111, v68
	v_add_u32_e32 v68, 16, v78
	v_mul_f32_e32 v144, 0.15915494, v0
	v_cvt_f32_i32_e32 v68, v68
	v_mul_f32_e32 v0, v144, v145
	v_floor_f32_e32 v0, v0
	v_fma_f32 v0, v144, v145, -v0
	v_sin_f32_e32 v99, v0
	v_cos_f32_e32 v98, v0
	v_mul_f32_e32 v0, 0xbed49a78, v68
	s_waitcnt vmcnt(5)
; __device__ __forceinline__ float bflo(unsigned w) { return __uint_as_float(w << 16); }
; __device__ __forceinline__ float bfhi(unsigned w) { return __uint_as_float(w & 0xffff0000u); }
; __device__ __forceinline__ void attn_item(const bf16_t* __restrict__ Qb, const bf16_t* __restrict__ Kh, const bf16_t* __restrict__ Vh, const bf16_t* __restrict__ Zb, ...
;     ...
;     for (int d0 = 0; d0 < 8; ++d0) qw[d0] = *reinterpret_cast<const u32x4*>(Qw + d0 * 16);
;     float ss = 0.f;
; #pragma unroll
;     for (int d0 = 0; d0 < 8; ++d0) { const float a0 = bflo(qw[d0].x), a1 = bfhi(qw[d0].x), a2 = bflo(qw[d0].y), a3 = bfhi(qw[d0].y), a4 = bflo(qw[d0].z), a5 = bfhi(qw[d0].z), a6 = bflo(qw[d0].w), a7 = bfhi(qw[d0].w);
;       ss += (a0 * a0 + a1 * a1) + (a2 * a2 + a3 * a3) + (a4 * a4 + a5 * a5) + (a6 * a6 + a7 * a7); }
;     { auto rr = __builtin_amdgcn_permlane32_swap(__float_as_uint(ss), __float_as_uint(ss), false, false); ss = __uint_as_float(rr[0]) + __uint_as_float(rr[1]); }
	v_lshlrev_b32_e32 v93, 16, v57
	v_and_b32_e32 v91, 0xffff0000, v57
	v_and_b32_e32 v155, 0xffff0000, v43
	v_and_b32_e32 v157, 0xffff0000, v42
	v_exp_f32_e32 v79, v0
	v_mov_b32_e32 v94, v93
	v_mov_b32_e32 v95, v91
	v_mul_f32_e32 v0, v91, v91
	v_lshlrev_b32_e32 v113, 16, v49
	v_and_b32_e32 v123, 0xffff0000, v49
	v_lshlrev_b32_e32 v57, 16, v43
	v_lshlrev_b32_e32 v49, 16, v42
	v_mov_b32_e32 v42, v155
	v_mov_b32_e32 v43, v157
	v_pk_fma_f32 v[150:151], v[94:95], v[94:95], v[0:1] op_sel_hi:[1,1,0]
	v_lshlrev_b32_e32 v103, 16, v56
	v_and_b32_e32 v95, 0xffff0000, v56
	v_lshlrev_b32_e32 v125, 16, v48
	v_and_b32_e32 v117, 0xffff0000, v48
	v_lshlrev_b32_e32 v56, 16, v39
	v_and_b32_e32 v154, 0xffff0000, v39
	v_lshlrev_b32_e32 v48, 16, v38
	v_and_b32_e32 v156, 0xffff0000, v38
	v_mov_b32_e32 v38, v57
	v_mov_b32_e32 v39, v49
	v_pk_mul_f32 v[42:43], v[42:43], v[42:43]
	v_and_b32_e32 v159, 0xffff0000, v41
	v_pk_fma_f32 v[38:39], v[38:39], v[38:39], v[42:43]
	v_lshlrev_b32_e32 v43, 16, v41
	v_and_b32_e32 v41, 0xffff0000, v40
	v_and_b32_e32 v118, 0xffff0000, v47
	v_lshlrev_b32_e32 v161, 16, v40
	v_mov_b32_e32 v162, v41
	v_mov_b32_e32 v163, v159
	v_and_b32_e32 v70, 0xffff0000, v63
	v_lshlrev_b32_e32 v72, 16, v62
	v_and_b32_e32 v62, 0xffff0000, v62
	v_lshlrev_b32_e32 v114, 16, v47
	v_and_b32_e32 v120, 0xffff0000, v46
	v_lshlrev_b32_e32 v42, 16, v37
	v_and_b32_e32 v158, 0xffff0000, v37
	v_lshlrev_b32_e32 v160, 16, v36
	v_and_b32_e32 v40, 0xffff0000, v36
	v_mov_b32_e32 v36, v161
	v_mov_b32_e32 v37, v43
	v_pk_mul_f32 v[162:163], v[162:163], v[162:163]
	v_mov_b32_e32 v164, v154
	v_mov_b32_e32 v165, v118
	v_lshlrev_b32_e32 v68, 16, v63
	v_mov_b32_e32 v74, v70
	v_mov_b32_e32 v75, v62
	v_lshlrev_b32_e32 v126, 16, v46
	v_and_b32_e32 v122, 0xffff0000, v45
	v_pk_fma_f32 v[36:37], v[36:37], v[36:37], v[162:163]
	v_mov_b32_e32 v162, v56
	v_mov_b32_e32 v163, v114
	v_pk_mul_f32 v[164:165], v[164:165], v[164:165]
	v_mov_b32_e32 v166, v156
	v_mov_b32_e32 v167, v120
	s_waitcnt vmcnt(4)
	v_lshlrev_b32_e32 v69, 16, v67
	v_and_b32_e32 v71, 0xffff0000, v67
	v_lshlrev_b32_e32 v73, 16, v66
	v_and_b32_e32 v63, 0xffff0000, v66
	v_mov_b32_e32 v66, v68
	v_mov_b32_e32 v67, v72
	v_pk_mul_f32 v[74:75], v[74:75], v[74:75]
	v_lshlrev_b32_e32 v112, 16, v45
	v_and_b32_e32 v116, 0xffff0000, v44
	v_pk_fma_f32 v[162:163], v[162:163], v[162:163], v[164:165]
	v_mov_b32_e32 v164, v48
	v_mov_b32_e32 v165, v126
	v_pk_mul_f32 v[166:167], v[166:167], v[166:167]
	v_mov_b32_e32 v168, v158
	v_mov_b32_e32 v169, v122
	v_pk_fma_f32 v[80:81], v[66:67], v[66:67], v[74:75]
	v_and_b32_e32 v66, 0xffff0000, v61
	v_lshlrev_b32_e32 v76, 16, v60
	v_and_b32_e32 v60, 0xffff0000, v60
	v_lshlrev_b32_e32 v124, 16, v44
	v_pk_fma_f32 v[164:165], v[164:165], v[164:165], v[166:167]
	v_mov_b32_e32 v166, v42
	v_mov_b32_e32 v167, v112
	v_pk_mul_f32 v[168:169], v[168:169], v[168:169]
	v_mov_b32_e32 v170, v40
	v_mov_b32_e32 v171, v116
	v_lshlrev_b32_e32 v74, 16, v61
	v_mov_b32_e32 v84, v60
	v_mov_b32_e32 v85, v66
	v_pk_fma_f32 v[166:167], v[166:167], v[166:167], v[168:169]
	v_mov_b32_e32 v168, v160
	v_mov_b32_e32 v169, v124
	v_pk_mul_f32 v[170:171], v[170:171], v[170:171]
	v_lshlrev_b32_e32 v75, 16, v65
	v_and_b32_e32 v67, 0xffff0000, v65
	v_lshlrev_b32_e32 v77, 16, v64
	v_and_b32_e32 v61, 0xffff0000, v64
	v_mov_b32_e32 v64, v76
	v_mov_b32_e32 v65, v74
	v_pk_mul_f32 v[84:85], v[84:85], v[84:85]
	v_pk_fma_f32 v[168:169], v[168:169], v[168:169], v[170:171]
	v_pk_fma_f32 v[64:65], v[64:65], v[64:65], v[84:85]
	v_lshlrev_b32_e32 v92, 16, v53
	v_and_b32_e32 v90, 0xffff0000, v53
	v_lshlrev_b32_e32 v102, 16, v52
	v_and_b32_e32 v94, 0xffff0000, v52
	v_mov_b32_e32 v52, v103
	v_mov_b32_e32 v53, v95
	v_mul_f32_e32 v0, v95, v95
	v_pk_add_f32 v[166:167], v[168:169], v[166:167]
	v_pk_add_f32 v[64:65], v[64:65], v[64:65] op_sel:[0,1] op_sel_hi:[1,0]
	v_and_b32_e32 v87, 0xffff0000, v58
	v_and_b32_e32 v86, 0xffff0000, v54
	v_pk_fma_f32 v[52:53], v[52:53], v[52:53], v[0:1] op_sel_hi:[1,1,0]
	v_and_b32_e32 v119, 0xffff0000, v51
	v_mov_b32_e32 v46, v113
	v_mov_b32_e32 v47, v123
	v_mul_f32_e32 v0, v123, v123
	v_pk_add_f32 v[36:37], v[36:37], v[36:37] op_sel:[0,1] op_sel_hi:[1,0]
	v_pk_add_f32 v[164:165], v[164:165], v[166:167]
	v_pk_add_f32 v[64:65], v[80:81], v[64:65] op_sel:[1,0] op_sel_hi:[0,1]
	v_lshlrev_b32_e32 v89, 16, v58
	v_lshlrev_b32_e32 v88, 16, v54
	v_lshlrev_b32_e32 v115, 16, v51
	v_and_b32_e32 v121, 0xffff0000, v50
	v_pk_fma_f32 v[46:47], v[46:47], v[46:47], v[0:1] op_sel_hi:[1,1,0]
	v_mov_b32_e32 v44, v125
	v_mov_b32_e32 v45, v117
	v_mul_f32_e32 v0, v117, v117
	v_pk_add_f32 v[36:37], v[38:39], v[36:37] op_sel:[1,0] op_sel_hi:[0,1]
	v_pk_add_f32 v[162:163], v[162:163], v[164:165]
	v_pk_mov_b32 v[164:165], v[118:119], v[86:87] op_sel:[1,0]
	v_pk_add_f32 v[64:65], v[80:81], v[64:65]
	v_lshlrev_b32_e32 v85, 16, v59
	v_lshlrev_b32_e32 v84, 16, v55
	v_and_b32_e32 v81, 0xffff0000, v59
	v_and_b32_e32 v80, 0xffff0000, v55
	v_pk_mul_f32 v[54:55], v[92:93], v[92:93]
	v_pk_mul_f32 v[58:59], v[90:91], v[90:91]
	v_lshlrev_b32_e32 v127, 16, v50
	v_pk_fma_f32 v[44:45], v[44:45], v[44:45], v[0:1] op_sel_hi:[1,1,0]
	v_pk_add_f32 v[36:37], v[38:39], v[36:37]
	v_pk_add_f32 v[38:39], v[162:163], v[162:163] op_sel:[0,1] op_sel_hi:[1,0]
	v_pk_mov_b32 v[162:163], v[114:115], v[88:89] op_sel:[1,0]
	v_pk_mul_f32 v[164:165], v[164:165], v[164:165]
	v_pk_mov_b32 v[166:167], v[120:121], v[94:95] op_sel:[1,0]
	v_pk_fma_f32 v[162:163], v[162:163], v[162:163], v[164:165]
	v_pk_mov_b32 v[164:165], v[126:127], v[102:103] op_sel:[1,0]
	v_pk_mul_f32 v[166:167], v[166:167], v[166:167]
	v_mov_b32_e32 v45, v54
	v_mov_b32_e32 v47, v58
	v_pk_mul_f32 v[146:147], v[84:85], v[84:85]
	v_pk_mul_f32 v[148:149], v[80:81], v[80:81]
	v_pk_fma_f32 v[164:165], v[164:165], v[164:165], v[166:167]
	v_pk_add_f32 v[44:45], v[44:45], v[46:47]
	v_mov_b32_e32 v39, v146
	v_pk_add_f32 v[44:45], v[164:165], v[44:45]
	v_mov_b32_e32 v37, v148
	v_pk_add_f32 v[44:45], v[162:163], v[44:45]
	v_pk_add_f32 v[36:37], v[38:39], v[36:37]
	v_pk_mul_f32 v[132:133], v[74:75], v[74:75]
	v_pk_add_f32 v[36:37], v[36:37], v[44:45]
	v_mov_b32_e32 v44, v81
	v_mov_b32_e32 v45, v63
	v_pk_mul_f32 v[134:135], v[66:67], v[66:67]
	v_mov_b32_e32 v38, v85
	v_mov_b32_e32 v39, v73
	v_pk_mul_f32 v[44:45], v[44:45], v[44:45]
	v_mov_b32_e32 v46, v87
	v_mov_b32_e32 v47, v61
	v_pk_fma_f32 v[38:39], v[38:39], v[38:39], v[44:45]
	v_mov_b32_e32 v44, v89
	v_mov_b32_e32 v45, v77
	v_pk_mul_f32 v[46:47], v[46:47], v[46:47]
	v_mov_b32_e32 v53, v133
	v_mov_b32_e32 v151, v135
	v_pk_mul_f32 v[128:129], v[68:69], v[68:69]
	v_pk_mul_f32 v[130:131], v[70:71], v[70:71]
	v_pk_add_f32 v[36:37], v[36:37], v[36:37] op_sel:[0,1] op_sel_hi:[1,0]
	v_pk_fma_f32 v[44:45], v[44:45], v[44:45], v[46:47]
	v_pk_add_f32 v[46:47], v[52:53], v[150:151]
	v_mov_b32_e32 v37, v129
	v_pk_add_f32 v[44:45], v[44:45], v[46:47]
	v_mov_b32_e32 v65, v131
	v_pk_add_f32 v[38:39], v[38:39], v[44:45]
	v_pk_add_f32 v[36:37], v[36:37], v[64:65]
	s_waitcnt vmcnt(2)
; __device__ __forceinline__ int lane_id_asm() { int r; asm volatile("v_mbcnt_lo_u32_b32 %0, -1, 0\n\tv_mbcnt_hi_u32_b32 %0, -1, %0" : "=v"(r)); return r; }
; __device__ __forceinline__ float bflo(unsigned w) { return __uint_as_float(w << 16); }
; __device__ __forceinline__ void attn_item(const bf16_t* __restrict__ Qb, const bf16_t* __restrict__ Kh, const bf16_t* __restrict__ Vh, const bf16_t* __restrict__ Zb, ...
;     ...
;     { auto rr = __builtin_amdgcn_permlane32_swap(__float_as_uint(ss), __float_as_uint(ss), false, false); ss = __uint_as_float(rr[0]) + __uint_as_float(rr[1]); }
;     const float rstd = __builtin_amdgcn_rsqf(ss * (1.0f / 128.0f) + NORM_EPS) * (SCALE * 1.4426950408889634f);
;     const int hq = lane_id_asm() >> 5;
;     const int spos = qpos0 + wid * QBLK + r32; const float prow = (float)(spos >> 6), pcol = (float)(spos & 63);
; #pragma unroll
;     for (int bb = 0; bb < 4; ++bb) { const int d1 = (bb & 1) + 4 * (bb >> 1), d2 = d1 + 2;
;       const float pos = (bb < 2) ? prow : pcol; const float* g1p = qg + d1 * 16 + hq * 8; const float* g2p = qg + d2 * 16 + hq * 8;
;       const f32x4 g1a = *(const f32x4*)g1p, g1b = *(const f32x4*)(g1p + 4), g2a = *(const f32x4*)g2p, g2b = *(const f32x4*)(g2p + 4);
;       float o1[8], o2[8];
; #pragma unroll
;       for (int e = 0; e < 8; ++e) { const unsigned w1 = (e < 2) ? qw[d1].x : (e < 4) ? qw[d1].y : (e < 6) ? qw[d1].z : qw[d1].w, w2 = (e < 2) ? qw[d2].x : (e < 4) ? qw[d2].y : (e < 6) ? qw[d2].z : qw[d2].w;
;         const float x1 = (e & 1) ? bfhi(w1) : bflo(w1), x2 = (e & 1) ? bfhi(w2) : bflo(w2); const float ga = (e < 4) ? g1a[e & 3] : g1b[e & 3], gb = (e < 4) ? g2a[e & 3] : g2b[e & 3];
;         const int fi = (d1 & 1) * 16 + hq * 8 + e; float rev = pos * (__builtin_amdgcn_exp2f(-(float)fi * (13.287712379549449f / 32.0f)) * 0.15915494309189535f); rev -= floorf(rev);
;         const float sn = sin_rev(rev), cs = cos_rev(rev), y1 = x1 * rstd * ga, y2 = x2 * rstd * gb; o1[e] = y1 * cs - y2 * sn; o2[e] = y2 * cs + y1 * sn; }
; #pragma unroll
;       for (int e = 0; e < 8; ++e) qn2 += o1[e] * o1[e] + o2[e] * o2[e];
;       u32x4 p1 = {cvtpk(o1[0], o1[1]), cvtpk(o1[2], o1[3]), cvtpk(o1[4], o1[5]), cvtpk(o1[6], o1[7])}, p2 = {cvtpk(o2[0], o2[1]), cvtpk(o2[2], o2[3]), cvtpk(o2[4], o2[5]), cvtpk(o2[6], o2[7])};
;       qr[d1] = *reinterpret_cast<bf16x8*>(&p1); qr[d2] = *reinterpret_cast<bf16x8*>(&p2); }
	v_mov_b32_e32 v50, v2
	v_pk_add_f32 v[36:37], v[36:37], v[38:39]
	v_mov_b32_e32 v128, v12
	v_pk_add_f32 v[36:37], v[36:37], v[36:37] op_sel:[0,1] op_sel_hi:[1,0]
	s_waitcnt vmcnt(1)
	v_mov_b32_e32 v129, v34
	v_mov_b32_e32 v0, v36
	s_nop 1
	v_permlane32_swap_b32_e32 v36, v0
	v_add_f32_e32 v0, v36, v0
	v_fmamk_f32 v0, v0, 0x3c000000, v217
	v_rsq_f32_e32 v0, v0
	v_mov_b32_e32 v36, v10
	v_mov_b32_e32 v37, v32
	v_mov_b32_e32 v32, v11
	v_mul_f32_e32 v0, 0x3e0293ee, v0
	v_pk_mul_f32 v[38:39], v[0:1], v[160:161] op_sel_hi:[0,1]
	v_pk_mul_f32 v[38:39], v[36:37], v[38:39]
	v_mov_b32_e32 v36, v105
	v_mov_b32_e32 v37, v104
	v_mul_f32_e32 v2, v39, v104
	v_pk_mul_f32 v[40:41], v[0:1], v[40:41] op_sel_hi:[0,1]
	v_pk_fma_f32 v[36:37], v[38:39], v[36:37], v[2:3] op_sel_hi:[1,1,0] neg_lo:[0,0,1] neg_hi:[0,0,1]
	v_mul_f32_e32 v2, v39, v105
	v_pk_mul_f32 v[10:11], v[32:33], v[40:41]
	v_pk_fma_f32 v[38:39], v[38:39], v[104:105], v[2:3] op_sel_hi:[1,1,0]
	v_mul_f32_e32 v2, v11, v83
	v_pk_fma_f32 v[32:33], v[10:11], v[82:83], v[2:3] op_sel_hi:[1,1,0] neg_lo:[0,0,1] neg_hi:[0,0,1]
	v_mov_b32_e32 v40, v83
	v_mov_b32_e32 v41, v82
	v_mul_f32_e32 v2, v11, v82
	v_pk_fma_f32 v[40:41], v[10:11], v[40:41], v[2:3] op_sel_hi:[1,1,0]
	v_pk_mul_f32 v[10:11], v[0:1], v[42:43] op_sel_hi:[0,1]
	v_pk_mul_f32 v[10:11], v[128:129], v[10:11]
	v_mov_b32_e32 v42, v107
	v_mov_b32_e32 v43, v106
	v_mul_f32_e32 v2, v11, v106
	v_pk_fma_f32 v[42:43], v[10:11], v[42:43], v[2:3] op_sel_hi:[1,1,0] neg_lo:[0,0,1] neg_hi:[0,0,1]
	v_mul_f32_e32 v2, v11, v107
	v_pk_fma_f32 v[44:45], v[10:11], v[106:107], v[2:3] op_sel_hi:[1,1,0]
	v_pk_mul_f32 v[10:11], v[0:1], v[158:159] op_sel_hi:[0,1]
	v_mov_b32_e32 v34, v13
	v_pk_mul_f32 v[10:11], v[34:35], v[10:11]
	v_mov_b32_e32 v12, v97
	v_mul_f32_e32 v2, v11, v97
	v_pk_fma_f32 v[34:35], v[10:11], v[96:97], v[2:3] op_sel_hi:[1,1,0] neg_lo:[0,0,1] neg_hi:[0,0,1]
	v_mov_b32_e32 v13, v96
	v_mul_f32_e32 v2, v11, v96
	s_waitcnt vmcnt(0)
	v_mov_b32_e32 v51, v6
	v_pk_fma_f32 v[46:47], v[10:11], v[12:13], v[2:3] op_sel_hi:[1,1,0]
	v_pk_mul_f32 v[10:11], v[0:1], v[48:49] op_sel_hi:[0,1]
	v_pk_mul_f32 v[10:11], v[50:51], v[10:11]
	v_mov_b32_e32 v12, v109
	v_mov_b32_e32 v13, v108
	v_mul_f32_e32 v2, v11, v108
	v_pk_fma_f32 v[48:49], v[10:11], v[12:13], v[2:3] op_sel_hi:[1,1,0] neg_lo:[0,0,1] neg_hi:[0,0,1]
	v_mul_f32_e32 v2, v11, v109
	v_pk_fma_f32 v[50:51], v[10:11], v[108:109], v[2:3] op_sel_hi:[1,1,0]
	v_pk_mul_f32 v[10:11], v[0:1], v[156:157] op_sel_hi:[0,1]
	v_mov_b32_e32 v6, v3
	v_pk_mul_f32 v[2:3], v[6:7], v[10:11]
	v_mov_b32_e32 v152, v4
	v_mul_f32_e32 v4, v3, v101
	v_pk_fma_f32 v[52:53], v[2:3], v[100:101], v[4:5] op_sel_hi:[1,1,0] neg_lo:[0,0,1] neg_hi:[0,0,1]
	v_mov_b32_e32 v6, v101
	v_mov_b32_e32 v7, v100
	v_mul_f32_e32 v4, v3, v100
	v_mov_b32_e32 v153, v8
	v_pk_fma_f32 v[54:55], v[2:3], v[6:7], v[4:5] op_sel_hi:[1,1,0]
	v_pk_mul_f32 v[2:3], v[0:1], v[56:57] op_sel_hi:[0,1]
	v_pk_mul_f32 v[2:3], v[152:153], v[2:3]
	v_mov_b32_e32 v6, v111
	v_mov_b32_e32 v7, v110
	v_mul_f32_e32 v4, v3, v110
	v_pk_fma_f32 v[56:57], v[2:3], v[6:7], v[4:5] op_sel_hi:[1,1,0] neg_lo:[0,0,1] neg_hi:[0,0,1]
	v_mul_f32_e32 v4, v3, v111
	v_pk_fma_f32 v[58:59], v[2:3], v[110:111], v[4:5] op_sel_hi:[1,1,0]
	v_pk_mul_f32 v[2:3], v[0:1], v[154:155] op_sel_hi:[0,1]
	v_mov_b32_e32 v8, v5
	v_pk_mul_f32 v[2:3], v[8:9], v[2:3]
	v_cvt_pk_bf16_f32 v152, v36, v32
	v_cvt_pk_bf16_f32 v153, v42, v34
	v_cvt_pk_bf16_f32 v154, v48, v52
	v_add_u32_e32 v96, 17, v78
	v_mul_f32_e32 v4, v3, v99
	v_pk_fma_f32 v[64:65], v[2:3], v[98:99], v[4:5] op_sel_hi:[1,1,0] neg_lo:[0,0,1] neg_hi:[0,0,1]
	v_mov_b32_e32 v4, v99
	v_mov_b32_e32 v5, v98
	v_mul_f32_e32 v6, v3, v98
	v_pk_fma_f32 v[82:83], v[2:3], v[4:5], v[6:7] op_sel_hi:[1,1,0]
	v_cvt_pk_bf16_f32 v155, v56, v64
	v_cvt_pk_bf16_f32 v148, v38, v40
	v_cvt_pk_bf16_f32 v149, v44, v46
	v_cvt_pk_bf16_f32 v150, v50, v54
	v_cvt_f32_i32_e32 v96, v96
	v_cvt_pk_bf16_f32 v151, v58, v82
	global_load_dwordx4 v[2:5], v[14:15], off offset:80
	global_load_dwordx4 v[6:9], v[14:15], off offset:64
	global_load_dwordx4 v[10:13], v[14:15], off offset:192
	global_load_dwordx4 v[128:131], v[14:15], off offset:208
	v_mul_f32_e32 v176, 0.15915494, v79
	v_mul_f32_e32 v96, 0xbed49a78, v96
	v_exp_f32_e32 v98, v96
	v_mul_f32_e32 v79, v176, v145
	v_floor_f32_e32 v79, v79
	v_fma_f32 v79, v176, v145, -v79
	v_mul_f32_e32 v177, 0.15915494, v98
	v_add_u32_e32 v98, 18, v78
	v_cvt_f32_i32_e32 v98, v98
	v_sin_f32_e32 v96, v79
	v_cos_f32_e32 v97, v79
	v_mul_f32_e32 v79, v177, v145
	v_floor_f32_e32 v79, v79
	v_fma_f32 v79, v177, v145, -v79
	v_mul_f32_e32 v98, 0xbed49a78, v98
	v_sin_f32_e32 v99, v79
	v_exp_f32_e32 v100, v98
	v_cos_f32_e32 v98, v79
	v_add_u32_e32 v79, 19, v78
	v_cvt_f32_i32_e32 v79, v79
	v_add_u32_e32 v104, 20, v78
	v_cvt_f32_i32_e32 v104, v104
	v_mul_f32_e32 v178, 0.15915494, v100
	v_mul_f32_e32 v79, 0xbed49a78, v79
	v_exp_f32_e32 v79, v79
	v_mul_f32_e32 v104, 0xbed49a78, v104
	v_exp_f32_e32 v104, v104
	v_mul_f32_e32 v100, v178, v145
	v_mul_f32_e32 v179, 0.15915494, v79
	v_mul_f32_e32 v79, v179, v145
	v_floor_f32_e32 v79, v79
	v_fma_f32 v79, v179, v145, -v79
	v_mul_f32_e32 v180, 0.15915494, v104
	v_sin_f32_e32 v107, v79
	v_cos_f32_e32 v106, v79
	v_add_u32_e32 v79, 21, v78
	v_mul_f32_e32 v104, v180, v145
	v_cvt_f32_i32_e32 v79, v79
	v_floor_f32_e32 v104, v104
	v_fma_f32 v104, v180, v145, -v104
	v_sin_f32_e32 v110, v104
	v_cos_f32_e32 v111, v104
	v_add_u32_e32 v104, 22, v78
	v_add_u32_e32 v78, 23, v78
	v_cvt_f32_i32_e32 v104, v104
	v_cvt_f32_i32_e32 v78, v78
	v_mul_f32_e32 v79, 0xbed49a78, v79
	v_exp_f32_e32 v79, v79
	v_mul_f32_e32 v104, 0xbed49a78, v104
	v_mul_f32_e32 v78, 0xbed49a78, v78
	v_exp_f32_e32 v104, v104
	v_exp_f32_e32 v78, v78
	v_mul_f32_e32 v181, 0.15915494, v79
	v_mul_f32_e32 v79, v181, v145
	v_floor_f32_e32 v79, v79
	v_fma_f32 v79, v181, v145, -v79
	v_mul_f32_e32 v182, 0.15915494, v104
	v_mul_f32_e32 v183, 0.15915494, v78
	v_sin_f32_e32 v133, v79
	v_cos_f32_e32 v132, v79
	v_mul_f32_e32 v79, v182, v145
	v_mul_f32_e32 v78, v183, v145
	v_floor_f32_e32 v79, v79
	v_floor_f32_e32 v78, v78
	v_fma_f32 v79, v182, v145, -v79
	v_fma_f32 v78, v183, v145, -v78
	v_sin_f32_e32 v134, v79
	v_cos_f32_e32 v135, v79
	v_sin_f32_e32 v147, v78
	v_cos_f32_e32 v146, v78
	v_pk_mul_f32 v[78:79], v[0:1], v[124:125] op_sel_hi:[0,1]
	v_floor_f32_e32 v100, v100
	v_fma_f32 v101, v178, v145, -v100
	v_sin_f32_e32 v100, v101
	v_cos_f32_e32 v101, v101
	v_pk_mul_f32 v[102:103], v[0:1], v[102:103] op_sel_hi:[0,1]
	v_pk_mul_f32 v[94:95], v[0:1], v[94:95] op_sel_hi:[0,1]
	s_waitcnt vmcnt(2)
; __device__ __forceinline__ unsigned cvtpk(float lo, float hi) { unsigned r; asm volatile("v_cvt_pk_bf16_f32 %0, %1, %2" : "=v"(r) : "v"(lo), "v"(hi)); return r; }
; __device__ __forceinline__ float bflo(unsigned w) { return __uint_as_float(w << 16); }
; __device__ __forceinline__ float bfhi(unsigned w) { return __uint_as_float(w & 0xffff0000u); }
; __device__ __forceinline__ float sin_rev(float rev) { return __builtin_amdgcn_sinf(rev); }
; __device__ __forceinline__ void attn_item(const bf16_t* __restrict__ Qb, const bf16_t* __restrict__ Kh, const bf16_t* __restrict__ Vh, const bf16_t* __restrict__ Zb, ...
;     ...
;     for (int bb = 0; bb < 4; ++bb) { const int d1 = (bb & 1) + 4 * (bb >> 1), d2 = d1 + 2;
;       const float pos = (bb < 2) ? prow : pcol; const float* g1p = qg + d1 * 16 + hq * 8; const float* g2p = qg + d2 * 16 + hq * 8;
;       const f32x4 g1a = *(const f32x4*)g1p, g1b = *(const f32x4*)(g1p + 4), g2a = *(const f32x4*)g2p, g2b = *(const f32x4*)(g2p + 4);
;       float o1[8], o2[8];
; #pragma unroll
;       for (int e = 0; e < 8; ++e) { const unsigned w1 = (e < 2) ? qw[d1].x : (e < 4) ? qw[d1].y : (e < 6) ? qw[d1].z : qw[d1].w, w2 = (e < 2) ? qw[d2].x : (e < 4) ? qw[d2].y : (e < 6) ? qw[d2].z : qw[d2].w;
;         const float x1 = (e & 1) ? bfhi(w1) : bflo(w1), x2 = (e & 1) ? bfhi(w2) : bflo(w2); const float ga = (e < 4) ? g1a[e & 3] : g1b[e & 3], gb = (e < 4) ? g2a[e & 3] : g2b[e & 3];
;         const int fi = (d1 & 1) * 16 + hq * 8 + e; float rev = pos * (__builtin_amdgcn_exp2f(-(float)fi * (13.287712379549449f / 32.0f)) * 0.15915494309189535f); rev -= floorf(rev);
;         const float sn = sin_rev(rev), cs = cos_rev(rev), y1 = x1 * rstd * ga, y2 = x2 * rstd * gb; o1[e] = y1 * cs - y2 * sn; o2[e] = y2 * cs + y1 * sn; }
; #pragma unroll
;       for (int e = 0; e < 8; ++e) qn2 += o1[e] * o1[e] + o2[e] * o2[e];
;       u32x4 p1 = {cvtpk(o1[0], o1[1]), cvtpk(o1[2], o1[3]), cvtpk(o1[4], o1[5]), cvtpk(o1[6], o1[7])}, p2 = {cvtpk(o2[0], o2[1]), cvtpk(o2[2], o2[3]), cvtpk(o2[4], o2[5]), cvtpk(o2[6], o2[7])};
;       qr[d1] = *reinterpret_cast<bf16x8*>(&p1); qr[d2] = *reinterpret_cast<bf16x8*>(&p2); }
;   }
;   const int sr = tid >> 4, sc = (tid & 15) * 8, vst0 = v_st_nat(sr, sc), vst1 = v_st_nat(32 + sr, sc), kst0 = KOFF + KSWZ(sr, sc * 2), kst1 = KOFF + KSWZ(32 + sr, sc * 2);
	v_mov_b32_e32 v104, v6
	s_waitcnt vmcnt(1)
	v_mov_b32_e32 v105, v10
	v_pk_mul_f32 v[104:105], v[78:79], v[104:105]
	v_mov_b32_e32 v78, v97
	v_mov_b32_e32 v79, v96
	v_mul_f32_e32 v6, v96, v105
	v_pk_fma_f32 v[78:79], v[78:79], v[104:105], v[6:7] op_sel_hi:[1,1,0] neg_lo:[0,0,1] neg_hi:[0,0,1]
	v_mul_f32_e32 v6, v97, v105
	v_pk_fma_f32 v[96:97], v[96:97], v[104:105], v[6:7] op_sel_hi:[1,1,0]
	v_pk_mul_f32 v[104:105], v[0:1], v[116:117] op_sel_hi:[0,1]
	v_mov_b32_e32 v10, v7
	v_pk_mul_f32 v[6:7], v[104:105], v[10:11]
	v_pk_mul_f32 v[76:77], v[0:1], v[76:77] op_sel_hi:[0,1]
	v_mul_f32_e32 v10, v99, v7
	v_pk_fma_f32 v[104:105], v[98:99], v[6:7], v[10:11] op_sel_hi:[1,1,0] neg_lo:[0,0,1] neg_hi:[0,0,1]
	v_mov_b32_e32 v10, v99
	v_mov_b32_e32 v11, v98
	v_mul_f32_e32 v98, v98, v7
	v_pk_fma_f32 v[108:109], v[10:11], v[6:7], v[98:99] op_sel_hi:[1,1,0]
	v_pk_mul_f32 v[6:7], v[0:1], v[112:113] op_sel_hi:[0,1]
	v_mov_b32_e32 v10, v8
	v_mov_b32_e32 v11, v12
	v_pk_mul_f32 v[6:7], v[6:7], v[10:11]
	v_mov_b32_e32 v10, v101
	v_mov_b32_e32 v11, v100
	v_mul_f32_e32 v8, v100, v7
	v_pk_fma_f32 v[112:113], v[10:11], v[6:7], v[8:9] op_sel_hi:[1,1,0] neg_lo:[0,0,1] neg_hi:[0,0,1]
	v_mul_f32_e32 v8, v101, v7
	v_pk_fma_f32 v[116:117], v[100:101], v[6:7], v[8:9] op_sel_hi:[1,1,0]
	v_pk_mul_f32 v[6:7], v[0:1], v[122:123] op_sel_hi:[0,1]
	v_mov_b32_e32 v12, v9
	v_pk_mul_f32 v[6:7], v[6:7], v[12:13]
	v_cvt_pk_bf16_f32 v160, v78, v104
	s_mulk_i32 s0, 0x2080
	v_mul_f32_e32 v8, v107, v7
	v_pk_fma_f32 v[122:123], v[106:107], v[6:7], v[8:9] op_sel_hi:[1,1,0] neg_lo:[0,0,1] neg_hi:[0,0,1]
	v_mov_b32_e32 v8, v107
	v_mov_b32_e32 v9, v106
	v_mul_f32_e32 v10, v106, v7
	v_pk_fma_f32 v[124:125], v[8:9], v[6:7], v[10:11] op_sel_hi:[1,1,0]
	v_pk_mul_f32 v[6:7], v[0:1], v[126:127] op_sel_hi:[0,1]
	v_mov_b32_e32 v8, v2
	s_waitcnt vmcnt(0)
	v_mov_b32_e32 v9, v128
	v_pk_mul_f32 v[6:7], v[6:7], v[8:9]
	v_mov_b32_e32 v8, v111
	v_mov_b32_e32 v9, v110
	v_mul_f32_e32 v2, v110, v7
	v_pk_fma_f32 v[98:99], v[8:9], v[6:7], v[2:3] op_sel_hi:[1,1,0] neg_lo:[0,0,1] neg_hi:[0,0,1]
	v_mul_f32_e32 v2, v111, v7
	v_pk_fma_f32 v[100:101], v[110:111], v[6:7], v[2:3] op_sel_hi:[1,1,0]
	v_pk_mul_f32 v[6:7], v[0:1], v[120:121] op_sel_hi:[0,1]
	v_mov_b32_e32 v128, v3
	v_pk_mul_f32 v[2:3], v[6:7], v[128:129]
	v_cvt_pk_bf16_f32 v161, v112, v122
	v_and_b32_e32 v128, 63, v136
	v_mul_f32_e32 v6, v133, v3
	v_pk_fma_f32 v[106:107], v[132:133], v[2:3], v[6:7] op_sel_hi:[1,1,0] neg_lo:[0,0,1] neg_hi:[0,0,1]
	v_mov_b32_e32 v6, v133
	v_mov_b32_e32 v7, v132
	v_mul_f32_e32 v8, v132, v3
	v_pk_fma_f32 v[110:111], v[6:7], v[2:3], v[8:9] op_sel_hi:[1,1,0]
	v_pk_mul_f32 v[2:3], v[0:1], v[114:115] op_sel_hi:[0,1]
	v_mov_b32_e32 v6, v4
	v_mov_b32_e32 v7, v130
	v_pk_mul_f32 v[2:3], v[2:3], v[6:7]
	v_mov_b32_e32 v6, v135
	v_mov_b32_e32 v7, v134
	v_mul_f32_e32 v4, v134, v3
	v_pk_fma_f32 v[114:115], v[6:7], v[2:3], v[4:5] op_sel_hi:[1,1,0] neg_lo:[0,0,1] neg_hi:[0,0,1]
	v_mul_f32_e32 v4, v135, v3
	v_pk_fma_f32 v[120:121], v[134:135], v[2:3], v[4:5] op_sel_hi:[1,1,0]
	v_pk_mul_f32 v[2:3], v[0:1], v[118:119] op_sel_hi:[0,1]
	v_mov_b32_e32 v130, v5
	v_pk_mul_f32 v[2:3], v[2:3], v[130:131]
	v_cvt_pk_bf16_f32 v162, v98, v106
	v_cvt_f32_ubyte0_e32 v189, v128
	v_mul_f32_e32 v4, v147, v3
	v_pk_fma_f32 v[118:119], v[146:147], v[2:3], v[4:5] op_sel_hi:[1,1,0] neg_lo:[0,0,1] neg_hi:[0,0,1]
	v_mov_b32_e32 v4, v147
	v_mov_b32_e32 v5, v146
	v_mul_f32_e32 v6, v146, v3
	v_pk_fma_f32 v[126:127], v[4:5], v[2:3], v[6:7] op_sel_hi:[1,1,0]
	v_cvt_pk_bf16_f32 v163, v114, v118
	v_cvt_pk_bf16_f32 v156, v96, v108
	v_cvt_pk_bf16_f32 v157, v116, v124
	v_cvt_pk_bf16_f32 v158, v100, v110
	v_mul_f32_e32 v130, v138, v189
	v_cvt_pk_bf16_f32 v159, v120, v126
	global_load_dwordx4 v[2:5], v[14:15], off offset:256
	global_load_dwordx4 v[6:9], v[14:15], off offset:384
	global_load_dwordx4 v[10:13], v[14:15], off offset:272
	global_load_dwordx4 v[164:167], v[14:15], off offset:400
	v_mul_f32_e32 v128, v137, v189
	v_floor_f32_e32 v130, v130
	v_floor_f32_e32 v128, v128
	v_fma_f32 v130, v138, v189, -v130
	v_mul_f32_e32 v138, v142, v189
	v_fma_f32 v129, v137, v189, -v128
	v_floor_f32_e32 v138, v138
	v_sin_f32_e32 v128, v129
	v_cos_f32_e32 v129, v129
	v_fma_f32 v138, v142, v189, -v138
	v_mul_f32_e32 v142, v144, v189
	v_floor_f32_e32 v142, v142
	v_fma_f32 v142, v144, v189, -v142
	v_sin_f32_e32 v131, v130
	v_cos_f32_e32 v130, v130
	v_mul_f32_e32 v132, v139, v189
	v_floor_f32_e32 v132, v132
	v_fma_f32 v133, v139, v189, -v132
	v_sin_f32_e32 v132, v133
	v_cos_f32_e32 v133, v133
	v_mul_f32_e32 v134, v140, v189
	v_floor_f32_e32 v134, v134
	v_fma_f32 v134, v140, v189, -v134
	v_sin_f32_e32 v135, v134
	v_cos_f32_e32 v134, v134
	v_mul_f32_e32 v136, v141, v189
	v_floor_f32_e32 v136, v136
	v_fma_f32 v137, v141, v189, -v136
	v_sin_f32_e32 v136, v137
	v_cos_f32_e32 v137, v137
	v_sin_f32_e32 v139, v138
	v_cos_f32_e32 v138, v138
	v_mul_f32_e32 v140, v143, v189
	v_floor_f32_e32 v140, v140
	v_fma_f32 v141, v143, v189, -v140
	v_sin_f32_e32 v140, v141
	v_cos_f32_e32 v141, v141
	v_sin_f32_e32 v143, v142
	v_cos_f32_e32 v142, v142
	s_add_u32 s0, s42, s0
	s_addc_u32 s1, s43, 0
	v_lshlrev_b32_e32 v206, 3, v186
	s_add_u32 s0, s0, s8
	s_addc_u32 s1, s1, 0
	v_pk_mul_f32 v[38:39], v[38:39], v[38:39]
	v_lshlrev_b32_e32 v221, 8, v187
	v_pk_fma_f32 v[36:37], v[36:37], v[36:37], v[38:39]
	v_pk_mul_f32 v[38:39], v[40:41], v[40:41]
	v_and_b32_e32 v208, 63, v186
	v_pk_fma_f32 v[32:33], v[32:33], v[32:33], v[38:39]
	v_and_b32_e32 v39, 24, v206
	v_pk_add_f32 v[32:33], v[36:37], v[32:33]
	v_pk_mul_f32 v[36:37], v[44:45], v[44:45]
	s_cmp_lg_u32 0, -1
	v_pk_fma_f32 v[36:37], v[42:43], v[42:43], v[36:37]
	s_mul_i32 s9, s6, 0x8200000
	v_pk_add_f32 v[32:33], v[36:37], v[32:33]
	v_pk_mul_f32 v[36:37], v[46:47], v[46:47]
	s_cselect_b32 s6, 0, 0
	v_pk_fma_f32 v[34:35], v[34:35], v[34:35], v[36:37]
	v_lshrrev_b32_e32 v36, 5, v186
	v_pk_add_f32 v[32:33], v[34:35], v[32:33]
	v_pk_mul_f32 v[34:35], v[50:51], v[50:51]
	v_bfe_u32 v37, v206, 5, 2
	v_pk_fma_f32 v[34:35], v[48:49], v[48:49], v[34:35]
	v_and_or_b32 v36, v36, s58, v37
	v_pk_add_f32 v[32:33], v[34:35], v[32:33]
	v_pk_mul_f32 v[34:35], v[54:55], v[54:55]
	v_mov_b32_e32 v244, 1.0
	v_pk_fma_f32 v[34:35], v[52:53], v[52:53], v[34:35]
	s_mov_b32 s76, 0x10000
	v_pk_add_f32 v[32:33], v[34:35], v[32:33]
	v_pk_mul_f32 v[34:35], v[58:59], v[58:59]
	v_pk_mul_f32 v[58:59], v[120:121], v[120:121]
	v_pk_fma_f32 v[34:35], v[56:57], v[56:57], v[34:35]
	s_mov_b32 s77, 0x8000
	s_waitcnt vmcnt(3)
; __device__ __forceinline__ unsigned cvtpk(float lo, float hi) { unsigned r; asm volatile("v_cvt_pk_bf16_f32 %0, %1, %2" : "=v"(r) : "v"(lo), "v"(hi)); return r; }
; __device__ __forceinline__ float bflo(unsigned w) { return __uint_as_float(w << 16); }
; __device__ __forceinline__ float bfhi(unsigned w) { return __uint_as_float(w & 0xffff0000u); }
; __device__ __forceinline__ float sin_rev(float rev) { return __builtin_amdgcn_sinf(rev); }
; __device__ __forceinline__ void attn_item(const bf16_t* __restrict__ Qb, const bf16_t* __restrict__ Kh, const bf16_t* __restrict__ Vh, const bf16_t* __restrict__ Zb, ...
;     ...
;     for (int bb = 0; bb < 4; ++bb) { const int d1 = (bb & 1) + 4 * (bb >> 1), d2 = d1 + 2;
;       const float pos = (bb < 2) ? prow : pcol; const float* g1p = qg + d1 * 16 + hq * 8; const float* g2p = qg + d2 * 16 + hq * 8;
;       const f32x4 g1a = *(const f32x4*)g1p, g1b = *(const f32x4*)(g1p + 4), g2a = *(const f32x4*)g2p, g2b = *(const f32x4*)(g2p + 4);
;       float o1[8], o2[8];
; #pragma unroll
;       for (int e = 0; e < 8; ++e) { const unsigned w1 = (e < 2) ? qw[d1].x : (e < 4) ? qw[d1].y : (e < 6) ? qw[d1].z : qw[d1].w, w2 = (e < 2) ? qw[d2].x : (e < 4) ? qw[d2].y : (e < 6) ? qw[d2].z : qw[d2].w;
;         const float x1 = (e & 1) ? bfhi(w1) : bflo(w1), x2 = (e & 1) ? bfhi(w2) : bflo(w2); const float ga = (e < 4) ? g1a[e & 3] : g1b[e & 3], gb = (e < 4) ? g2a[e & 3] : g2b[e & 3];
;         const int fi = (d1 & 1) * 16 + hq * 8 + e; float rev = pos * (__builtin_amdgcn_exp2f(-(float)fi * (13.287712379549449f / 32.0f)) * 0.15915494309189535f); rev -= floorf(rev);
;         const float sn = sin_rev(rev), cs = cos_rev(rev), y1 = x1 * rstd * ga, y2 = x2 * rstd * gb; o1[e] = y1 * cs - y2 * sn; o2[e] = y2 * cs + y1 * sn; }
; #pragma unroll
;       for (int e = 0; e < 8; ++e) qn2 += o1[e] * o1[e] + o2[e] * o2[e];
;       u32x4 p1 = {cvtpk(o1[0], o1[1]), cvtpk(o1[2], o1[3]), cvtpk(o1[4], o1[5]), cvtpk(o1[6], o1[7])}, p2 = {cvtpk(o2[0], o2[1]), cvtpk(o2[2], o2[3]), cvtpk(o2[4], o2[5]), cvtpk(o2[6], o2[7])};
;       qr[d1] = *reinterpret_cast<bf16x8*>(&p1); qr[d2] = *reinterpret_cast<bf16x8*>(&p2); }
;   }
;   const int sr = tid >> 4, sc = (tid & 15) * 8, vst0 = v_st_nat(sr, sc), vst1 = v_st_nat(32 + sr, sc), kst0 = KOFF + KSWZ(sr, sc * 2), kst1 = KOFF + KSWZ(32 + sr, sc * 2);
;   const int vb0 = (int)(uintptr_t)lds + v_rd_base(lane);
	v_mov_b32_e32 v144, v2
	s_waitcnt vmcnt(2)
	v_mov_b32_e32 v145, v6
	v_pk_mul_f32 v[144:145], v[102:103], v[144:145]
	v_mov_b32_e32 v102, v129
	v_mov_b32_e32 v103, v128
	v_mul_f32_e32 v2, v128, v145
	v_pk_fma_f32 v[102:103], v[102:103], v[144:145], v[2:3] op_sel_hi:[1,1,0] neg_lo:[0,0,1] neg_hi:[0,0,1]
	v_mul_f32_e32 v2, v129, v145
	v_mov_b32_e32 v6, v3
	v_pk_fma_f32 v[128:129], v[128:129], v[144:145], v[2:3] op_sel_hi:[1,1,0]
	v_pk_mul_f32 v[2:3], v[94:95], v[6:7]
	v_mul_f32_e32 v144, v177, v189
	v_mul_f32_e32 v6, v131, v3
	v_pk_fma_f32 v[94:95], v[130:131], v[2:3], v[6:7] op_sel_hi:[1,1,0] neg_lo:[0,0,1] neg_hi:[0,0,1]
	v_mov_b32_e32 v6, v131
	v_mov_b32_e32 v7, v130
	v_mul_f32_e32 v130, v130, v3
	v_pk_fma_f32 v[130:131], v[6:7], v[2:3], v[130:131] op_sel_hi:[1,1,0]
	v_pk_mul_f32 v[2:3], v[0:1], v[92:93] op_sel_hi:[0,1]
	v_mov_b32_e32 v6, v4
	v_mov_b32_e32 v7, v8
	v_pk_mul_f32 v[2:3], v[2:3], v[6:7]
	v_mov_b32_e32 v6, v133
	v_mov_b32_e32 v7, v132
	v_mul_f32_e32 v4, v132, v3
	v_pk_fma_f32 v[92:93], v[6:7], v[2:3], v[4:5] op_sel_hi:[1,1,0] neg_lo:[0,0,1] neg_hi:[0,0,1]
	v_mul_f32_e32 v4, v133, v3
	v_pk_fma_f32 v[132:133], v[132:133], v[2:3], v[4:5] op_sel_hi:[1,1,0]
	v_pk_mul_f32 v[2:3], v[0:1], v[90:91] op_sel_hi:[0,1]
	v_mov_b32_e32 v8, v5
	v_pk_mul_f32 v[2:3], v[2:3], v[8:9]
	v_cvt_pk_bf16_f32 v168, v102, v94
	v_floor_f32_e32 v144, v144
	v_mul_f32_e32 v4, v135, v3
	v_pk_fma_f32 v[90:91], v[134:135], v[2:3], v[4:5] op_sel_hi:[1,1,0] neg_lo:[0,0,1] neg_hi:[0,0,1]
	v_mov_b32_e32 v4, v135
	v_mov_b32_e32 v5, v134
	v_mul_f32_e32 v6, v134, v3
	v_pk_fma_f32 v[134:135], v[4:5], v[2:3], v[6:7] op_sel_hi:[1,1,0]
	v_pk_mul_f32 v[2:3], v[0:1], v[88:89] op_sel_hi:[0,1]
	s_waitcnt vmcnt(1)
	v_mov_b32_e32 v4, v10
	s_waitcnt vmcnt(0)
	v_mov_b32_e32 v5, v164
	v_pk_mul_f32 v[2:3], v[2:3], v[4:5]
	v_mov_b32_e32 v4, v137
	v_mov_b32_e32 v5, v136
	v_mul_f32_e32 v6, v136, v3
	v_pk_fma_f32 v[88:89], v[4:5], v[2:3], v[6:7] op_sel_hi:[1,1,0] neg_lo:[0,0,1] neg_hi:[0,0,1]
	v_mul_f32_e32 v4, v137, v3
	v_pk_fma_f32 v[136:137], v[136:137], v[2:3], v[4:5] op_sel_hi:[1,1,0]
	v_pk_mul_f32 v[2:3], v[0:1], v[86:87] op_sel_hi:[0,1]
	v_mov_b32_e32 v164, v11
	v_pk_mul_f32 v[2:3], v[2:3], v[164:165]
	v_cvt_pk_bf16_f32 v169, v92, v90
	v_fma_f32 v144, v177, v189, -v144
	v_mul_f32_e32 v4, v139, v3
	v_pk_fma_f32 v[86:87], v[138:139], v[2:3], v[4:5] op_sel_hi:[1,1,0] neg_lo:[0,0,1] neg_hi:[0,0,1]
	v_mov_b32_e32 v4, v139
	v_mov_b32_e32 v5, v138
	v_mul_f32_e32 v6, v138, v3
	v_pk_fma_f32 v[138:139], v[4:5], v[2:3], v[6:7] op_sel_hi:[1,1,0]
	v_pk_mul_f32 v[2:3], v[0:1], v[84:85] op_sel_hi:[0,1]
	v_mov_b32_e32 v4, v12
	v_mov_b32_e32 v5, v166
	v_pk_mul_f32 v[2:3], v[2:3], v[4:5]
	v_mov_b32_e32 v4, v141
	v_mov_b32_e32 v5, v140
	v_mul_f32_e32 v6, v140, v3
	v_pk_fma_f32 v[84:85], v[4:5], v[2:3], v[6:7] op_sel_hi:[1,1,0] neg_lo:[0,0,1] neg_hi:[0,0,1]
	v_mul_f32_e32 v4, v141, v3
	v_pk_fma_f32 v[140:141], v[140:141], v[2:3], v[4:5] op_sel_hi:[1,1,0]
	v_pk_mul_f32 v[2:3], v[0:1], v[80:81] op_sel_hi:[0,1]
	v_mov_b32_e32 v166, v13
	v_pk_mul_f32 v[2:3], v[2:3], v[166:167]
	v_cvt_pk_bf16_f32 v170, v88, v86
	v_sin_f32_e32 v147, v144
	v_mul_f32_e32 v4, v143, v3
	v_pk_fma_f32 v[80:81], v[142:143], v[2:3], v[4:5] op_sel_hi:[1,1,0] neg_lo:[0,0,1] neg_hi:[0,0,1]
	v_mov_b32_e32 v4, v143
	v_mov_b32_e32 v5, v142
	v_mul_f32_e32 v6, v142, v3
	v_pk_fma_f32 v[142:143], v[4:5], v[2:3], v[6:7] op_sel_hi:[1,1,0]
	v_cvt_pk_bf16_f32 v171, v84, v80
	v_cvt_pk_bf16_f32 v164, v128, v130
	v_cvt_pk_bf16_f32 v165, v132, v134
	v_cvt_pk_bf16_f32 v166, v136, v138
	v_cos_f32_e32 v146, v144
	v_cvt_pk_bf16_f32 v167, v140, v142
	global_load_dwordx4 v[2:5], v[14:15], off offset:320
	global_load_dwordx4 v[6:9], v[14:15], off offset:448
	global_load_dwordx4 v[10:13], v[14:15], off offset:336
	global_load_dwordx4 v[172:175], v[14:15], off offset:464
	v_mul_f32_e32 v144, v178, v189
	v_mul_f32_e32 v14, v176, v189
	v_floor_f32_e32 v144, v144
	v_floor_f32_e32 v14, v14
	v_fma_f32 v144, v178, v189, -v144
	v_fma_f32 v15, v176, v189, -v14
	v_sin_f32_e32 v176, v144
	v_cos_f32_e32 v177, v144
	v_mul_f32_e32 v144, v179, v189
	v_floor_f32_e32 v144, v144
	v_fma_f32 v144, v179, v189, -v144
	v_sin_f32_e32 v179, v144
	v_cos_f32_e32 v178, v144
	v_mul_f32_e32 v144, v180, v189
	v_floor_f32_e32 v144, v144
	v_fma_f32 v144, v180, v189, -v144
	v_sin_f32_e32 v184, v144
	v_cos_f32_e32 v185, v144
	v_mul_f32_e32 v144, v181, v189
	v_floor_f32_e32 v144, v144
	v_fma_f32 v144, v181, v189, -v144
	v_sin_f32_e32 v191, v144
	v_cos_f32_e32 v190, v144
	v_mul_f32_e32 v144, v182, v189
	v_floor_f32_e32 v144, v144
	v_fma_f32 v144, v182, v189, -v144
	v_sin_f32_e32 v192, v144
	v_cos_f32_e32 v193, v144
	v_mul_f32_e32 v144, v183, v189
	v_sin_f32_e32 v14, v15
	v_cos_f32_e32 v15, v15
	v_floor_f32_e32 v144, v144
	v_fma_f32 v144, v183, v189, -v144
	v_sin_f32_e32 v195, v144
	v_cos_f32_e32 v194, v144
	v_ashrrev_i32_e32 v189, 4, v186
	v_add_u32_e32 v207, 32, v189
	v_pk_add_f32 v[32:33], v[34:35], v[32:33]
	v_pk_mul_f32 v[34:35], v[82:83], v[82:83]
	v_lshlrev_b32_e32 v38, 5, v189
	v_pk_fma_f32 v[34:35], v[64:65], v[64:65], v[34:35]
	v_and_or_b32 v38, v38, s59, v39
	v_pk_add_f32 v[32:33], v[34:35], v[32:33]
	v_pk_mul_f32 v[34:35], v[96:97], v[96:97]
	v_lshlrev_b32_e32 v38, 1, v38
	v_pk_fma_f32 v[34:35], v[78:79], v[78:79], v[34:35]
	v_lshl_or_b32 v228, v36, 9, v38
	v_pk_add_f32 v[32:33], v[34:35], v[32:33]
	v_pk_mul_f32 v[34:35], v[108:109], v[108:109]
	v_lshrrev_b32_e32 v36, 1, v207
	v_pk_fma_f32 v[34:35], v[104:105], v[104:105], v[34:35]
	v_and_or_b32 v36, v36, s58, v37
	v_lshlrev_b32_e32 v82, 4, v186
	v_add_u32_e32 v108, 0, v228
	v_pk_add_f32 v[32:33], v[34:35], v[32:33]
	v_pk_mul_f32 v[34:35], v[116:117], v[116:117]
	v_lshl_or_b32 v229, v36, 9, v38
	v_lshlrev_b32_e32 v36, 8, v189
	v_and_b32_e32 v38, 0xf0, v186
	v_lshlrev_b32_e32 v39, 8, v207
	v_pk_fma_f32 v[34:35], v[112:113], v[112:113], v[34:35]
	v_add_u32_e32 v83, 0, v221
	v_pk_add_f32 v[32:33], v[34:35], v[32:33]
	v_pk_mul_f32 v[34:35], v[124:125], v[124:125]
	v_add_u32_e32 v109, 0, v229
	v_pk_fma_f32 v[34:35], v[122:123], v[122:123], v[34:35]
	v_pk_mul_f32 v[78:79], v[126:127], v[126:127]
	v_pk_add_f32 v[32:33], v[34:35], v[32:33]
	v_pk_mul_f32 v[34:35], v[100:101], v[100:101]
	s_mov_b32 s78, -1
	v_pk_fma_f32 v[34:35], v[98:99], v[98:99], v[34:35]
	v_mov_b32_e32 v219, 0
	v_pk_add_f32 v[32:33], v[34:35], v[32:33]
	v_pk_mul_f32 v[34:35], v[110:111], v[110:111]
	s_waitcnt vmcnt(3)
; __device__ __forceinline__ unsigned cvtpk(float lo, float hi) { unsigned r; asm volatile("v_cvt_pk_bf16_f32 %0, %1, %2" : "=v"(r) : "v"(lo), "v"(hi)); return r; }
; __device__ __forceinline__ float bflo(unsigned w) { return __uint_as_float(w << 16); }
; __device__ __forceinline__ float bfhi(unsigned w) { return __uint_as_float(w & 0xffff0000u); }
; __device__ __forceinline__ float sin_rev(float rev) { return __builtin_amdgcn_sinf(rev); }
; __device__ __forceinline__ float cos_rev(float rev) { return __builtin_amdgcn_cosf(rev); }
; __device__ __forceinline__ int v_st_nat(int k, int c) { return ((k >> 3) * 4 + (c >> 5)) * 512 + ((k & 7) * 32 + (c & 31)) * 2; }
; #define SWAIT() asm volatile("s_waitcnt vmcnt(0)" ::: "memory")
; __device__ __forceinline__ void attn_item(const bf16_t* __restrict__ Qb, const bf16_t* __restrict__ Kh, const bf16_t* __restrict__ Vh, const bf16_t* __restrict__ Zb, ...
;     ...
;         const float x1 = (e & 1) ? bfhi(w1) : bflo(w1), x2 = (e & 1) ? bfhi(w2) : bflo(w2); const float ga = (e < 4) ? g1a[e & 3] : g1b[e & 3], gb = (e < 4) ? g2a[e & 3] : g2b[e & 3];
;         const int fi = (d1 & 1) * 16 + hq * 8 + e; float rev = pos * (__builtin_amdgcn_exp2f(-(float)fi * (13.287712379549449f / 32.0f)) * 0.15915494309189535f); rev -= floorf(rev);
;         const float sn = sin_rev(rev), cs = cos_rev(rev), y1 = x1 * rstd * ga, y2 = x2 * rstd * gb; o1[e] = y1 * cs - y2 * sn; o2[e] = y2 * cs + y1 * sn; }
; #pragma unroll
;       for (int e = 0; e < 8; ++e) qn2 += o1[e] * o1[e] + o2[e] * o2[e];
;       u32x4 p1 = {cvtpk(o1[0], o1[1]), cvtpk(o1[2], o1[3]), cvtpk(o1[4], o1[5]), cvtpk(o1[6], o1[7])}, p2 = {cvtpk(o2[0], o2[1]), cvtpk(o2[2], o2[3]), cvtpk(o2[4], o2[5]), cvtpk(o2[6], o2[7])};
;       qr[d1] = *reinterpret_cast<bf16x8*>(&p1); qr[d2] = *reinterpret_cast<bf16x8*>(&p2); }
;   }
;   const int sr = tid >> 4, sc = (tid & 15) * 8, vst0 = v_st_nat(sr, sc), vst1 = v_st_nat(32 + sr, sc), kst0 = KOFF + KSWZ(sr, sc * 2), kst1 = KOFF + KSWZ(32 + sr, sc * 2);
;   const int vb0 = (int)(uintptr_t)lds + v_rd_base(lane);
;   struct { bf16x8 vs0, vs1, ks0, ks1; } sr_;
;     ...
;   f32x16 pA0, pA1, pB0, pB1; float alA, alB; VF8 vfa; bf16x8 pa0, pa1, pa2, pa3; const int NT = seq / KVBLK;
;   int s_prev = 0, s_cur = SLOT, s_next = 2 * SLOT;
;   SLOAD(0); SWAIT(); SWRITE(0); __syncthreads();
	v_mov_b32_e32 v144, v2
	s_waitcnt vmcnt(2)
	v_mov_b32_e32 v145, v6
	v_pk_mul_f32 v[144:145], v[76:77], v[144:145]
	v_mov_b32_e32 v76, v15
	v_mov_b32_e32 v77, v14
	v_mul_f32_e32 v2, v14, v145
	v_pk_fma_f32 v[76:77], v[76:77], v[144:145], v[2:3] op_sel_hi:[1,1,0] neg_lo:[0,0,1] neg_hi:[0,0,1]
	v_mul_f32_e32 v2, v15, v145
	v_pk_fma_f32 v[144:145], v[14:15], v[144:145], v[2:3] op_sel_hi:[1,1,0]
	v_pk_mul_f32 v[14:15], v[0:1], v[60:61] op_sel_hi:[0,1]
	v_mov_b32_e32 v6, v3
	v_pk_mul_f32 v[2:3], v[14:15], v[6:7]
	v_pk_fma_f32 v[34:35], v[106:107], v[106:107], v[34:35]
	v_mul_f32_e32 v6, v147, v3
	v_pk_fma_f32 v[60:61], v[146:147], v[2:3], v[6:7] op_sel_hi:[1,1,0] neg_lo:[0,0,1] neg_hi:[0,0,1]
	v_mov_b32_e32 v6, v147
	v_mov_b32_e32 v7, v146
	v_mul_f32_e32 v14, v146, v3
	v_pk_fma_f32 v[146:147], v[6:7], v[2:3], v[14:15] op_sel_hi:[1,1,0]
	v_pk_mul_f32 v[2:3], v[0:1], v[74:75] op_sel_hi:[0,1]
	v_mov_b32_e32 v6, v4
	v_mov_b32_e32 v7, v8
	v_pk_mul_f32 v[2:3], v[2:3], v[6:7]
	v_mov_b32_e32 v6, v177
	v_mov_b32_e32 v7, v176
	v_mul_f32_e32 v4, v176, v3
	v_pk_fma_f32 v[74:75], v[6:7], v[2:3], v[4:5] op_sel_hi:[1,1,0] neg_lo:[0,0,1] neg_hi:[0,0,1]
	v_mul_f32_e32 v4, v177, v3
	v_pk_fma_f32 v[180:181], v[176:177], v[2:3], v[4:5] op_sel_hi:[1,1,0]
	v_pk_mul_f32 v[2:3], v[0:1], v[66:67] op_sel_hi:[0,1]
	v_mov_b32_e32 v8, v5
	v_pk_mul_f32 v[2:3], v[2:3], v[8:9]
	s_waitcnt vmcnt(0)
	v_mov_b32_e32 v15, v174
	v_mul_f32_e32 v4, v179, v3
	v_pk_fma_f32 v[66:67], v[178:179], v[2:3], v[4:5] op_sel_hi:[1,1,0] neg_lo:[0,0,1] neg_hi:[0,0,1]
	v_mov_b32_e32 v4, v179
	v_mov_b32_e32 v5, v178
	v_mul_f32_e32 v6, v178, v3
	v_pk_fma_f32 v[182:183], v[4:5], v[2:3], v[6:7] op_sel_hi:[1,1,0]
	v_pk_mul_f32 v[2:3], v[0:1], v[72:73] op_sel_hi:[0,1]
	v_mov_b32_e32 v4, v10
	v_mov_b32_e32 v5, v172
	v_pk_mul_f32 v[6:7], v[0:1], v[62:63] op_sel_hi:[0,1]
	v_mov_b32_e32 v172, v11
	v_pk_mul_f32 v[2:3], v[2:3], v[4:5]
	v_mov_b32_e32 v4, v185
	v_mov_b32_e32 v5, v184
	v_pk_mul_f32 v[6:7], v[6:7], v[172:173]
	v_mov_b32_e32 v10, v191
	v_mov_b32_e32 v11, v190
	v_pk_mul_f32 v[62:63], v[0:1], v[70:71] op_sel_hi:[0,1]
	v_mov_b32_e32 v174, v13
	v_pk_mul_f32 v[4:5], v[4:5], v[2:3]
	v_pk_mul_f32 v[8:9], v[190:191], v[6:7]
	v_pk_mul_f32 v[6:7], v[10:11], v[6:7]
	v_pk_mul_f32 v[10:11], v[0:1], v[68:69] op_sel_hi:[0,1]
	v_mov_b32_e32 v14, v12
	v_pk_mul_f32 v[12:13], v[62:63], v[174:175]
	v_mov_b32_e32 v62, v195
	v_mov_b32_e32 v63, v194
	v_pk_mul_f32 v[2:3], v[184:185], v[2:3]
	v_pk_mul_f32 v[10:11], v[10:11], v[14:15]
	v_mov_b32_e32 v14, v193
	v_mov_b32_e32 v15, v192
	v_pk_mul_f32 v[68:69], v[194:195], v[12:13]
	v_pk_mul_f32 v[12:13], v[62:63], v[12:13]
	v_mov_b32_e32 v62, v8
	v_mov_b32_e32 v63, v4
	v_mov_b32_e32 v4, v9
	v_pk_mul_f32 v[14:15], v[14:15], v[10:11]
	v_pk_add_f32 v[62:63], v[62:63], v[4:5] neg_lo:[0,1] neg_hi:[0,1]
	v_mov_b32_e32 v4, v6
	v_mov_b32_e32 v5, v2
	v_mov_b32_e32 v2, v7
	v_pk_mul_f32 v[10:11], v[192:193], v[10:11]
	v_pk_add_f32 v[72:73], v[4:5], v[2:3]
	v_mov_b32_e32 v2, v68
	v_mov_b32_e32 v3, v14
	v_mov_b32_e32 v14, v69
	v_pk_add_f32 v[68:69], v[2:3], v[14:15] neg_lo:[0,1] neg_hi:[0,1]
	v_mov_b32_e32 v2, v12
	v_mov_b32_e32 v3, v10
	v_mov_b32_e32 v10, v13
	v_and_b32_e32 v70, 0x78, v206
	v_mov_b32_e32 v71, v1
	v_pk_add_f32 v[184:185], v[2:3], v[10:11]
	v_mad_i64_i32 v[2:3], s[36:37], v189, s61, v[70:71]
	v_lshl_add_u64 v[2:3], v[2:3], 1, s[0:1]
	v_cvt_pk_bf16_f32 v176, v76, v60
	v_cvt_pk_bf16_f32 v177, v74, v66
	v_cvt_pk_bf16_f32 v178, v63, v62
	v_cvt_pk_bf16_f32 v179, v69, v68
	v_cvt_pk_bf16_f32 v172, v144, v146
	v_cvt_pk_bf16_f32 v173, v180, v182
	v_cvt_pk_bf16_f32 v174, v73, v72
	v_cvt_pk_bf16_f32 v175, v185, v184
	global_load_dwordx4 v[190:193], v[2:3], off offset:2560
	v_mad_i64_i32 v[4:5], s[36:37], v207, s61, v[70:71]
	v_lshl_add_u64 v[4:5], v[4:5], 1, s[0:1]
	global_load_dwordx4 v[194:197], v[4:5], off offset:2560
	global_load_dwordx4 v[198:201], v[2:3], off offset:2048
	global_load_dwordx4 v[202:205], v[4:5], off offset:2048
	v_lshlrev_b32_e32 v37, 1, v70
	s_waitcnt vmcnt(0)
	v_bitop3_b32 v231, v37, v36, v38 bitop3:0xde
	v_bitop3_b32 v232, v39, v37, v38 bitop3:0xf6
	v_add_u32_e32 v112, 0, v231
	v_add_u32_e32 v113, 0, v232
	v_pk_add_f32 v[56:57], v[34:35], v[32:33]
	v_and_b32_e32 v0, 0x3fffffc0, v186
	v_mov_b32_e32 v14, v1
	v_mov_b32_e32 v15, v1
	v_lshl_add_u32 v213, v0, 2, s56
	v_mov_b32_e32 v0, v1
	v_mov_b32_e32 v2, v1
	v_mov_b32_e32 v3, v1
	v_mov_b32_e32 v4, v1
	v_mov_b32_e32 v5, v1
	v_mov_b32_e32 v6, v1
	v_mov_b32_e32 v7, v1
	v_mov_b32_e32 v8, v1
	v_mov_b32_e32 v9, v1
	v_mov_b32_e32 v10, v1
	v_mov_b32_e32 v11, v1
	v_mov_b32_e32 v12, v1
	v_mov_b32_e32 v13, v1
	v_or_b32_e32 v106, 0xc0, v212
	v_or_b32_e32 v107, 0xe0, v212
	v_lshl_add_u32 v220, v187, 2, v213
	s_waitcnt vmcnt(3)
	ds_write_b128 v108, v[190:193]
	v_and_b32_e32 v190, 0xf0, v82
	v_bitop3_b32 v234, v188, v190, 16 bitop3:0x6c
	v_add_u32_e32 v36, v83, v234
	s_waitcnt vmcnt(2)
	ds_write_b128 v109, v[194:197]
	s_waitcnt vmcnt(1)
	ds_write_b128 v112, v[198:201] offset:16384
	s_waitcnt vmcnt(0)
	ds_write_b128 v113, v[202:205] offset:16384
	s_waitcnt lgkmcnt(0)
	s_barrier
; #define SLOAD(k0) do { sr_.vs0 = *(const bf16x8*)(&Vh[(long)((k0) + sr) * LDK + sc]); sr_.vs1 = *(const bf16x8*)(&Vh[(long)((k0) + 32 + sr) * LDK + sc]); \
;     sr_.ks0 = *(const bf16x8*)(&Kh[(long)((k0) + sr) * LDK + sc]); sr_.ks1 = *(const bf16x8*)(&Kh[(long)((k0) + 32 + sr) * LDK + sc]); } while (0)
; #define SWRITE(so) do { *(bf16x8*)(lds + (so) + vst0) = sr_.vs0; *(bf16x8*)(lds + (so) + vst1) = sr_.vs1;          \
;     *(bf16x8*)(lds + (so) + kst0) = sr_.ks0; *(bf16x8*)(lds + (so) + kst1) = sr_.ks1; } while (0)
; #define SWAIT() asm volatile("s_waitcnt vmcnt(0)" ::: "memory")
; __device__ __forceinline__ void qkt(f32x16& p0, f32x16& p1, const bf16_t* Ks, const bf16x8* qr, const f32x16& negm, int r32, int hi) {
; #pragma unroll
;   for (int d0 = 0; d0 < 8; ++d0) { int cb = (d0 * 16 + hi * 8) * 2;
;     bf16x8 b0 = *reinterpret_cast<const bf16x8*>((const char*)Ks + KSWZ(r32, cb));
;     bf16x8 b1 = *reinterpret_cast<const bf16x8*>((const char*)Ks + KSWZ(32 + r32, cb));
;     if (d0 == 0) { p0 = __builtin_amdgcn_mfma_f32_32x32x16_bf16(b0, qr[0], negm, 0, 0, 0); p1 = __builtin_amdgcn_mfma_f32_32x32x16_bf16(b1, qr[0], negm, 0, 0, 0); }
;     else { p0 = __builtin_amdgcn_mfma_f32_32x32x16_bf16(b0, qr[d0], p0, 0, 0, 0); p1 = __builtin_amdgcn_mfma_f32_32x32x16_bf16(b1, qr[d0], p1, 0, 0, 0); } }
; }
; __device__ __forceinline__ void attn_item(const bf16_t* __restrict__ Qb, const bf16_t* __restrict__ Kh, const bf16_t* __restrict__ Vh, const bf16_t* __restrict__ Zb, ...
;     ...
;   SLOAD(0); SWAIT(); SWRITE(0); __syncthreads();
;   SLOAD(KVBLK);
;   qkt(pA0, pA1, (const bf16_t*)(lds + KOFF), qr, negm, r32, hi); partialSM<true>(pA0, pA1, m_reg, negm, alA);
	ds_read_b128 v[48:51], v36 offset:24576
	ds_read_b128 v[52:55], v36 offset:16384
	s_waitcnt lgkmcnt(0)
	v_mfma_f32_32x32x16_bf16 v[32:47], v[52:55], v[152:155], v[16:31]
	v_fma_f32 v52, v114, v114, v58
	v_fma_f32 v53, v115, v115, v59
	v_bitop3_b32 v233, v212, v190, 32 bitop3:0x36
	v_add_f32_e64 v64, v52, v56
	v_add_f32_e64 v65, v53, v57
	v_add_u32_e32 v56, v83, v233
	ds_read_b128 v[52:55], v56 offset:24576
	ds_read_b128 v[56:59], v56 offset:16384
	v_bitop3_b32 v230, v212, v190, 64 bitop3:0x36
	v_bitop3_b32 v227, v212, v190, s62 bitop3:0x36
	v_mfma_f32_32x32x16_bf16 v[16:31], v[48:51], v[152:155], v[16:31]
	v_fma_f32 v48, v118, v118, v78
	v_fma_f32 v49, v119, v119, v79
	v_mul_f32_e64 v50, v128, v128
	v_mul_f32_e64 v51, v129, v129
	v_add_f32_e64 v48, v48, v64
	v_add_f32_e64 v49, v49, v65
	v_pk_fma_f32 v[50:51], v[102:103], v[102:103], v[50:51]
	v_bitop3_b32 v226, v212, v190, s63 bitop3:0x36
	v_pk_add_f32 v[48:49], v[48:49], v[50:51]
	v_pk_mul_f32 v[50:51], v[130:131], v[130:131]
	s_waitcnt lgkmcnt(0)
	v_mfma_f32_32x32x16_bf16 v[32:47], v[56:59], v[160:163], v[32:47]
	v_fma_f32 v50, v94, v94, v50
	v_fma_f32 v51, v95, v95, v51
	v_add_u32_e32 v56, v83, v230
	v_add_f32_e64 v64, v50, v48
	v_add_f32_e64 v65, v51, v49
	v_pk_mul_f32 v[48:49], v[132:133], v[132:133]
	v_bitop3_b32 v225, v212, v190, s64 bitop3:0x36
	v_pk_fma_f32 v[78:79], v[92:93], v[92:93], v[48:49]
	ds_read_b128 v[48:51], v56 offset:24576
	ds_read_b128 v[56:59], v56 offset:16384
	v_mfma_f32_32x32x16_bf16 v[16:31], v[52:55], v[160:163], v[16:31]
	v_mul_f32_e64 v54, v134, v134
	v_mul_f32_e64 v55, v135, v135
	v_add_f32_e64 v52, v78, v64
	v_add_f32_e64 v53, v79, v65
	v_fma_f32 v54, v90, v90, v54
	v_fma_f32 v55, v91, v91, v55
	v_bitop3_b32 v224, v212, v190, s60 bitop3:0x36
	v_pk_add_f32 v[52:53], v[54:55], v[52:53]
	v_pk_mul_f32 v[54:55], v[136:137], v[136:137]
	v_bitop3_b32 v223, v212, v190, s59 bitop3:0x36
	v_pk_fma_f32 v[54:55], v[88:89], v[88:89], v[54:55]
	s_waitcnt lgkmcnt(0)
	v_mfma_f32_32x32x16_bf16 v[32:47], v[56:59], v[148:151], v[32:47]
	v_add_f32_e64 v52, v54, v52
	v_add_f32_e64 v53, v55, v53
	v_mul_f32_e64 v54, v138, v138
	v_mul_f32_e64 v55, v139, v139
	v_add_u32_e32 v56, v83, v227
	v_pk_fma_f32 v[54:55], v[86:87], v[86:87], v[54:55]
	v_bitop3_b32 v236, v212, v221, v190 bitop3:0xde
	v_pk_add_f32 v[64:65], v[54:55], v[52:53]
	ds_read_b128 v[52:55], v56 offset:24576
	ds_read_b128 v[56:59], v56 offset:16384
	v_mfma_f32_32x32x16_bf16 v[16:31], v[48:51], v[148:151], v[16:31]
	v_mul_f32_e64 v48, v140, v140
	v_mul_f32_e64 v49, v141, v141
	v_mul_f32_e64 v50, v142, v142
	v_mul_f32_e64 v51, v143, v143
	v_fma_f32 v48, v84, v84, v48
	v_fma_f32 v49, v85, v85, v49
	v_pk_fma_f32 v[50:51], v[80:81], v[80:81], v[50:51]
	v_pk_add_f32 v[48:49], v[48:49], v[64:65]
	v_bitop3_b32 v242, v106, v221, v190 bitop3:0xde
	v_pk_add_f32 v[48:49], v[50:51], v[48:49]
	s_waitcnt lgkmcnt(0)
	v_mfma_f32_32x32x16_bf16 v[32:47], v[56:59], v[156:159], v[32:47]
	v_mul_f32_e64 v50, v144, v144
	v_mul_f32_e64 v51, v145, v145
	v_add_u32_e32 v56, v83, v226
	v_fma_f32 v50, v76, v76, v50
	v_fma_f32 v51, v77, v77, v51
	v_pk_mul_f32 v[76:77], v[146:147], v[146:147]
	v_pk_add_f32 v[64:65], v[48:49], v[50:51]
	ds_read_b128 v[48:51], v56 offset:24576
	ds_read_b128 v[56:59], v56 offset:16384
	v_bitop3_b32 v243, v107, v221, v190 bitop3:0xde
	v_mfma_f32_32x32x16_bf16 v[16:31], v[52:55], v[156:159], v[16:31]
	v_fma_f32 v52, v60, v60, v76
	v_fma_f32 v53, v61, v61, v77
	v_mul_f32_e64 v54, v180, v180
	v_mul_f32_e64 v55, v181, v181
	v_add_f32_e64 v52, v52, v64
	v_add_f32_e64 v53, v53, v65
	v_pk_fma_f32 v[54:55], v[74:75], v[74:75], v[54:55]
	s_nop 0
	v_pk_add_f32 v[52:53], v[54:55], v[52:53]
	v_pk_mul_f32 v[54:55], v[182:183], v[182:183]
	s_waitcnt lgkmcnt(0)
	v_mfma_f32_32x32x16_bf16 v[32:47], v[56:59], v[168:171], v[32:47]
	v_fma_f32 v54, v66, v66, v54
	v_fma_f32 v55, v67, v67, v55
	v_add_u32_e32 v56, v83, v225
	v_add_f32_e64 v60, v54, v52
	v_add_f32_e64 v61, v55, v53
	v_pk_mul_f32 v[52:53], v[72:73], v[72:73]
	s_nop 0
	v_pk_fma_f32 v[62:63], v[62:63], v[62:63], v[52:53]
	ds_read_b128 v[52:55], v56 offset:24576
	ds_read_b128 v[56:59], v56 offset:16384
	v_mfma_f32_32x32x16_bf16 v[16:31], v[48:51], v[168:171], v[16:31]
	v_add_f32_e64 v48, v63, v60
	v_add_f32_e64 v49, v62, v61
	v_mul_f32_e64 v50, v184, v184
	v_mul_f32_e64 v51, v185, v185
	v_add_f32_e64 v48, v62, v48
	v_add_f32_e64 v49, v63, v49
	v_pk_fma_f32 v[50:51], v[68:69], v[68:69], v[50:51]
	v_lshlrev_b32_e32 v60, 3, v208
	v_pk_add_f32 v[48:49], v[50:51], v[48:49] op_sel:[1,0] op_sel_hi:[0,1]
	v_pk_add_f32 v[64:65], v[50:51], v[48:49]
	s_waitcnt lgkmcnt(0)
	v_mfma_f32_32x32x16_bf16 v[32:47], v[56:59], v[176:179], v[32:47]
	v_and_b32_e32 v48, 0xc0, v82
	v_add_u32_e32 v56, v83, v224
	v_and_or_b32 v61, v60, 24, v48
	v_lshlrev_b32_e32 v62, 1, v186
	ds_read_b128 v[48:51], v56 offset:24576
	ds_read_b128 v[56:59], v56 offset:16384
	v_or_b32_e32 v65, 0xa0, v212
	v_bitop3_b32 v241, v65, v221, v190 bitop3:0xde
	v_mfma_f32_32x32x16_bf16 v[16:31], v[52:55], v[176:179], v[16:31]
	v_and_b32_e32 v52, 32, v62
	v_and_b32_e32 v53, 0x100, v60
	v_or3_b32 v52, v61, v52, v53
	v_add_u32_e32 v235, s6, v52
	v_add_u32_e32 v52, 64, v189
	v_mad_i64_i32 v[52:53], s[6:7], v52, s61, v[70:71]
	v_add_u32_e32 v62, 0x60, v189
	s_waitcnt lgkmcnt(0)
	v_mfma_f32_32x32x16_bf16 v[32:47], v[56:59], v[164:167], v[32:47]
	v_lshl_add_u64 v[60:61], v[52:53], 1, s[0:1]
	v_add_u32_e32 v56, v83, v223
	ds_read_b128 v[52:55], v56 offset:24576
	ds_read_b128 v[56:59], v56 offset:16384
	v_mfma_f32_32x32x16_bf16 v[16:31], v[48:51], v[164:167], v[16:31]
	v_mad_i64_i32 v[48:49], s[6:7], v62, s61, v[70:71]
	v_lshl_add_u64 v[66:67], v[48:49], 1, s[0:1]
	global_load_dwordx4 v[48:51], v[60:61], off offset:2560
	s_nop 0
	global_load_dwordx4 v[60:63], v[60:61], off offset:2048
	s_nop 0
	global_load_dwordx4 v[98:101], v[66:67], off offset:2560
	global_load_dwordx4 v[102:105], v[66:67], off offset:2048
	v_cmp_gt_u32_e64 s[6:7], 32, v208
	s_waitcnt lgkmcnt(0)
; #define SWRITE(so) do { *(bf16x8*)(lds + (so) + vst0) = sr_.vs0; *(bf16x8*)(lds + (so) + vst1) = sr_.vs1;          \
;     *(bf16x8*)(lds + (so) + kst0) = sr_.ks0; *(bf16x8*)(lds + (so) + kst1) = sr_.ks1; } while (0)
; #define SWAIT() asm volatile("s_waitcnt vmcnt(0)" ::: "memory")
; template <bool FIRST, bool DOEXP = true>
; __device__ __forceinline__ void partialSM(f32x16& p0, f32x16& p1, float& m_reg, f32x16& negm, float& alpha, const bool track = true) {
;     ...
;   float pmax = p0[0];
; #pragma unroll
;   for (int r = 1; r < 16; ++r) pmax = fmaxf(pmax, p0[r]);
; #pragma unroll
;   for (int r = 0; r < 16; ++r) pmax = fmaxf(pmax, p1[r]);
;   { auto rr = __builtin_amdgcn_permlane32_swap(__float_as_uint(pmax), __float_as_uint(pmax), false, false);
;     pmax = fmaxf(__uint_as_float(rr[0]), __uint_as_float(rr[1])); }
;   if (!FIRST && __builtin_expect(__all(pmax <= THRL), 1)) { alpha = 1.f; }
;   else { const float dl = FIRST ? pmax : fmaxf(pmax, 0.f); m_reg += dl; alpha = FIRST ? 1.f : __builtin_amdgcn_exp2f(-dl);
; #pragma unroll
;     for (int r = 0; r < 16; ++r) { p0[r] -= dl; p1[r] -= dl; }
; #pragma unroll
;     for (int r = 0; r < 16; ++r) negm[r] = -m_reg;
;     asm volatile("" : "+v"(negm)); }
;   if (DOEXP) {
; #pragma unroll
;     for (int r = 0; r < 16; ++r) p0[r] = __builtin_amdgcn_exp2f(p0[r]); }
; __device__ __forceinline__ void attn_item(const bf16_t* __restrict__ Qb, const bf16_t* __restrict__ Kh, const bf16_t* __restrict__ Vh, const bf16_t* __restrict__ Zb, ...
;     ...
;   qkt(pA0, pA1, (const bf16_t*)(lds + KOFF), qr, negm, r32, hi); partialSM<true>(pA0, pA1, m_reg, negm, alA);
;   { auto rr = __builtin_amdgcn_permlane32_swap(__float_as_uint(qn2), __float_as_uint(qn2), false, false); qn2 = __uint_as_float(rr[0]) + __uint_as_float(rr[1]); }
;   const bool track = !__all(__builtin_sqrtf(qn2) * kmaxg - m_reg <= 90.f);
;   SWAIT(); SWRITE(SLOT); __syncthreads();
	v_mfma_f32_32x32x16_bf16 v[32:47], v[56:59], v[172:175], v[32:47]
	v_or_b32_e32 v56, 32, v212
	v_or_b32_e32 v57, 64, v212
	v_or_b32_e32 v58, 0x60, v212
	v_or_b32_e32 v59, 0x80, v212
	v_bitop3_b32 v237, v56, v221, v190 bitop3:0xde
	v_bitop3_b32 v238, v57, v221, v190 bitop3:0xde
	v_bitop3_b32 v239, v58, v221, v190 bitop3:0xde
	v_mfma_f32_32x32x16_bf16 v[16:31], v[52:55], v[172:175], v[16:31]
	s_nop 3
	v_max_f32_e32 v52, v32, v33
	v_max3_f32 v52, v52, v34, v35
	v_max3_f32 v52, v52, v36, v37
	v_max3_f32 v52, v52, v38, v39
	v_max3_f32 v52, v52, v40, v41
	v_max3_f32 v52, v52, v42, v43
	v_max3_f32 v52, v52, v44, v45
	v_max3_f32 v52, v52, v46, v47
	v_max3_f32 v52, v52, v16, v17
	v_max3_f32 v52, v52, v18, v19
	v_max3_f32 v52, v52, v20, v21
	v_max3_f32 v52, v52, v22, v23
	v_max3_f32 v52, v52, v24, v25
	v_max3_f32 v52, v52, v26, v27
	v_max3_f32 v52, v52, v28, v29
	v_max3_f32 v52, v52, v30, v31
	v_mov_b32_e32 v53, v52
	s_nop 1
	v_permlane32_swap_b32_e32 v52, v53
	v_max_f32_e32 v52, v52, v53
	v_sub_f32_e32 v82, v16, v52
	v_mov_b32_e32 v16, v64
	s_nop 1
	v_permlane32_swap_b32_e32 v64, v16
	v_add_f32_e32 v16, v64, v16
	v_sub_f32_e32 v83, v17, v52
	v_mul_f32_e32 v17, 0x4f800000, v16
	v_cmp_gt_f32_e32 vcc, s65, v16
	v_sub_f32_e32 v84, v18, v52
	v_sub_f32_e32 v85, v19, v52
	v_cndmask_b32_e32 v16, v16, v17, vcc
	v_sqrt_f32_e32 v17, v16
	v_add_f32_e32 v222, 0, v52
	v_sub_f32_e32 v32, v32, v52
	v_sub_f32_e32 v33, v33, v52
	v_add_u32_e32 v18, -1, v17
	v_fma_f32 v19, -v18, v17, v16
	v_cmp_ge_f32_e64 s[0:1], 0, v19
	v_add_u32_e32 v19, 1, v17
	v_sub_f32_e32 v34, v34, v52
	v_cndmask_b32_e64 v18, v17, v18, s[0:1]
	v_fma_f32 v17, -v19, v17, v16
	v_cmp_lt_f32_e64 s[0:1], 0, v17
	v_sub_f32_e32 v35, v35, v52
	v_sub_f32_e32 v36, v36, v52
	v_cndmask_b32_e64 v17, v18, v19, s[0:1]
	v_mul_f32_e32 v18, 0x37800000, v17
	v_cndmask_b32_e32 v17, v17, v18, vcc
	v_cmp_class_f32_e32 vcc, v16, v218
	v_sub_f32_e32 v37, v37, v52
	v_sub_f32_e32 v38, v38, v52
	v_cndmask_b32_e32 v16, v17, v16, vcc
	v_fma_f32 v16, v216, v16, -v222
	v_cmp_ge_f32_e32 vcc, s66, v16
	s_cmp_lg_u64 vcc, exec
	s_cselect_b64 s[0:1], -1, 0
	s_or_b32 s8, s9, s8
	v_sub_f32_e32 v39, v39, v52
	v_sub_f32_e32 v40, v40, v52
	v_sub_f32_e32 v41, v41, v52
	v_sub_f32_e32 v42, v42, v52
	v_sub_f32_e32 v43, v43, v52
	v_sub_f32_e32 v44, v44, v52
	v_sub_f32_e32 v45, v45, v52
	v_sub_f32_e32 v46, v46, v52
	v_sub_f32_e32 v47, v47, v52
	v_xor_b32_e32 v66, 0x80000000, v222
	v_mov_b32_e32 v16, s8
	v_mov_b32_e32 v17, v1
	v_and_b32_e32 v18, 15, v186
	v_mov_b32_e32 v67, v66
	v_mov_b32_e32 v68, v66
	v_mov_b32_e32 v69, v66
	v_mov_b32_e32 v70, v66
	v_mov_b32_e32 v71, v66
	v_mov_b32_e32 v72, v66
	v_mov_b32_e32 v73, v66
	v_mov_b32_e32 v74, v66
	v_mov_b32_e32 v75, v66
	v_mov_b32_e32 v76, v66
	v_mov_b32_e32 v77, v66
	v_mov_b32_e32 v78, v66
	v_mov_b32_e32 v79, v66
	v_mov_b32_e32 v80, v66
	v_mov_b32_e32 v81, v66
	v_exp_f32_e32 v114, v32
	v_exp_f32_e32 v115, v33
	v_exp_f32_e32 v116, v34
	v_exp_f32_e32 v117, v35
	v_exp_f32_e32 v118, v36
	v_exp_f32_e32 v119, v37
	v_exp_f32_e32 v120, v38
	v_exp_f32_e32 v121, v39
	v_exp_f32_e32 v122, v40
	v_exp_f32_e32 v123, v41
	v_exp_f32_e32 v124, v42
	v_exp_f32_e32 v125, v43
	v_exp_f32_e32 v126, v44
	v_exp_f32_e32 v127, v45
	v_exp_f32_e32 v128, v46
	v_exp_f32_e32 v129, v47
	v_mad_i64_i32 v[16:17], s[8:9], v189, s51, v[16:17]
	v_lshlrev_b32_e32 v18, 4, v18
	v_mov_b32_e32 v19, v1
	v_sub_f32_e32 v97, v31, v52
	v_sub_f32_e32 v96, v30, v52
	v_sub_f32_e32 v95, v29, v52
	v_sub_f32_e32 v94, v28, v52
	v_sub_f32_e32 v93, v27, v52
	v_sub_f32_e32 v92, v26, v52
	v_sub_f32_e32 v91, v25, v52
	v_sub_f32_e32 v90, v24, v52
	v_sub_f32_e32 v89, v23, v52
	v_sub_f32_e32 v88, v22, v52
	v_sub_f32_e32 v87, v21, v52
	v_sub_f32_e32 v86, v20, v52
	s_waitcnt vmcnt(0)
	s_waitcnt vmcnt(3)
	ds_write_b128 v108, v[48:51] offset:32768
	s_waitcnt vmcnt(1)
	ds_write_b128 v109, v[98:101] offset:32768
	ds_write_b128 v112, v[60:63] offset:49152
	s_waitcnt vmcnt(0)
	ds_write_b128 v113, v[102:105] offset:49152
	v_bitop3_b32 v240, v59, v221, v190 bitop3:0xde
	v_lshl_add_u64 v[16:17], v[16:17], 0, v[18:19]
	v_mov_b64_e32 v[64:65], v[14:15]
	v_mov_b64_e32 v[48:49], v[14:15]
	v_mov_b64_e32 v[32:33], v[14:15]
	v_lshl_add_u64 v[214:215], s[20:21], 0, v[16:17]
	v_mov_b64_e32 v[62:63], v[12:13]
	v_mov_b64_e32 v[60:61], v[10:11]
	v_mov_b64_e32 v[58:59], v[8:9]
	v_mov_b64_e32 v[56:57], v[6:7]
	v_mov_b64_e32 v[54:55], v[4:5]
	v_mov_b64_e32 v[52:53], v[2:3]
	v_mov_b64_e32 v[50:51], v[0:1]
	v_mov_b64_e32 v[46:47], v[12:13]
	v_mov_b64_e32 v[44:45], v[10:11]
	v_mov_b64_e32 v[42:43], v[8:9]
	v_mov_b64_e32 v[40:41], v[6:7]
	v_mov_b64_e32 v[38:39], v[4:5]
	v_mov_b64_e32 v[36:37], v[2:3]
	v_mov_b64_e32 v[34:35], v[0:1]
	v_mov_b64_e32 v[30:31], v[12:13]
	v_mov_b64_e32 v[28:29], v[10:11]
	v_mov_b64_e32 v[26:27], v[8:9]
	v_mov_b64_e32 v[24:25], v[6:7]
	v_mov_b64_e32 v[22:23], v[4:5]
	v_mov_b64_e32 v[20:21], v[2:3]
	v_mov_b64_e32 v[18:19], v[0:1]
	v_mov_b64_e32 v[16:17], v[14:15]
	v_mov_b64_e32 v[14:15], v[12:13]
	v_mov_b64_e32 v[12:13], v[10:11]
	v_mov_b64_e32 v[10:11], v[8:9]
	v_mov_b64_e32 v[8:9], v[6:7]
	v_mov_b64_e32 v[6:7], v[4:5]
	v_mov_b64_e32 v[4:5], v[2:3]
	v_mov_b64_e32 v[2:3], v[0:1]
	v_add_co_u32_e32 v248, vcc, s67, v214
	s_nop 1
	v_addc_co_u32_e32 v249, vcc, -1, v215, vcc
	v_add_co_u32_e32 v250, vcc, s68, v214
	s_nop 1
	v_addc_co_u32_e32 v251, vcc, -1, v215, vcc
	global_load_dwordx4 v[180:183], v[248:249], off
	global_load_dwordx4 v[184:187], v[248:249], off offset:-512
	global_load_dwordx4 v[192:195], v[250:251], off
	global_load_dwordx4 v[188:191], v[250:251], off offset:-512
	v_add_u32_e32 v252, 0x10000, v228
	v_add_u32_e32 v253, 0x10000, v229
	v_add_u32_e32 v254, 0x10000, v231
	v_add_u32_e32 v255, 0x10000, v232
	s_waitcnt vmcnt(0)
; #define SBAR() __builtin_amdgcn_sched_barrier(0)
; #define SLOAD(k0) do { sr_.vs0 = *(const bf16x8*)(&Vh[(long)((k0) + sr) * LDK + sc]); sr_.vs1 = *(const bf16x8*)(&Vh[(long)((k0) + 32 + sr) * LDK + sc]); \
;     sr_.ks0 = *(const bf16x8*)(&Kh[(long)((k0) + sr) * LDK + sc]); sr_.ks1 = *(const bf16x8*)(&Kh[(long)((k0) + 32 + sr) * LDK + sc]); } while (0)
; #define SWRITE(so) do { *(bf16x8*)(lds + (so) + vst0) = sr_.vs0; *(bf16x8*)(lds + (so) + vst1) = sr_.vs1;          \
;     *(bf16x8*)(lds + (so) + kst0) = sr_.ks0; *(bf16x8*)(lds + (so) + kst1) = sr_.ks1; } while (0)
; #define SWAIT() asm volatile("s_waitcnt vmcnt(0)" ::: "memory")
; __device__ __forceinline__ void attn_item(const bf16_t* __restrict__ Qb, const bf16_t* __restrict__ Kh, const bf16_t* __restrict__ Vh, const bf16_t* __restrict__ Zb, ...
;     ...
;   SWAIT(); SWRITE(SLOT); __syncthreads();
;   for (int j = 1; j + 1 < NT; j += 2) {
;     SBAR(); SLOAD((j + 1) * KVBLK); SBAR();
;     qkt_fin(pB0, pB1, (const bf16_t*)(lds + s_cur + KOFF), qr, negm, r32, hi, pA0, pA1, alA, l_reg, pa0, pa1, pa2, pa3, vfa, vb0 + s_prev); SBAR();
	ds_write_b128 v252, v[180:183]
	ds_write_b128 v253, v[192:195]
	ds_write_b128 v254, v[184:187] offset:16384
	ds_write_b128 v255, v[188:191] offset:16384
	v_mbcnt_lo_u32_b32 v248, -1, 0
	v_mbcnt_hi_u32_b32 v248, -1, v248
	s_lshr_b32 s79, s33, 6
	s_lshl_b32 s100, s79, 10
	s_lshl_b32 s101, s79, 11
	s_mov_b32 s76, 0x82000
	s_mov_b32 s77, 0
	v_and_b32_e32 v249, 15, v248
	v_lshrrev_b32_e32 v250, 4, v248
	v_lshl_add_u32 v250, s79, 2, v250
	v_and_b32_e32 v251, 15, v250
	v_xor_b32_e32 v251, v249, v251
	v_sub_u32_e32 v251, v251, v249
	v_lshlrev_b32_e32 v251, 4, v251
	v_add_u32_e32 v252, 0xfffbee00, v251
	v_ashrrev_i32_e32 v253, 31, v252
	v_and_b32_e32 v254, 31, v248
	v_lshrrev_b32_e32 v254, 2, v254
	v_lshl_add_u32 v254, s79, 3, v254
	v_sub_u32_e32 v254, v254, v250
	v_add_u32_e32 v254, 0xffffffe0, v254
	v_mov_b32_e32 v255, 0x2080
	v_mul_lo_u32 v254, v254, v255
	v_lshrrev_b32_e32 v255, 5, v248
	v_lshl_add_u32 v254, v255, 6, v254
	v_and_b32_e32 v255, 3, v248
	v_lshl_add_u32 v254, v255, 4, v254
	v_lshlrev_b32_e32 v255, 4, v249
	v_sub_u32_e32 v254, v254, v255
	s_waitcnt lgkmcnt(0)
	v_lshl_add_u64 v[180:181], v[214:215], 0, v[252:253]
	v_ashrrev_i32_e32 v255, 31, v254
	v_add_co_u32_e32 v182, vcc, 0x41000, v180
	s_nop 1
	v_addc_co_u32_e32 v183, vcc, 0, v181, vcc
	v_lshl_add_u64 v[214:215], v[214:215], 0, v[254:255]
	v_readfirstlane_b32 s82, v180
	v_readfirstlane_b32 s83, v181
	s_sub_u32 s82, s82, 0x400000
	s_subb_u32 s83, s83, 0
	v_subrev_u32_e32 v180, s82, v180
	v_subrev_u32_e32 v182, s82, v182
	v_subrev_u32_e32 v214, s82, v214
	s_mov_b32 s96, 0x8000
	v_mov_b32_e32 v184, v236
	v_mov_b32_e32 v185, v237
	v_mov_b32_e32 v186, v238
	v_mov_b32_e32 v187, v239
	v_mov_b32_e32 v188, v240
	v_mov_b32_e32 v189, v241
	v_mov_b32_e32 v190, v242
	v_mov_b32_e32 v191, v243
	s_mov_b32 s8, 0
	s_cmp_ge_u32 s33, 0x100
	s_cbranch_scc1 .Lh2_pro
	s_barrier
; #define SBAR() __builtin_amdgcn_sched_barrier(0)
; __device__ __forceinline__ unsigned cvtpk(float lo, float hi) { unsigned r; asm volatile("v_cvt_pk_bf16_f32 %0, %1, %2" : "=v"(r) : "v"(lo), "v"(hi)); return r; }
; template <bool FIRST, bool DOEXP = true>
; __device__ __forceinline__ void partialSM(f32x16& p0, f32x16& p1, float& m_reg, f32x16& negm, float& alpha, const bool track = true) {
;     ...
;   float pmax = p0[0];
; #pragma unroll
;   for (int r = 1; r < 16; ++r) pmax = fmaxf(pmax, p0[r]);
; #pragma unroll
;   for (int r = 0; r < 16; ++r) pmax = fmaxf(pmax, p1[r]);
;   { auto rr = __builtin_amdgcn_permlane32_swap(__float_as_uint(pmax), __float_as_uint(pmax), false, false);
;     pmax = fmaxf(__uint_as_float(rr[0]), __uint_as_float(rr[1])); }
;   if (!FIRST && __builtin_expect(__all(pmax <= THRL), 1)) { alpha = 1.f; }
; __device__ __forceinline__ void qkt_fin(f32x16& n0, f32x16& n1, const bf16_t* Ks, const bf16x8* qr, const f32x16& negm, int r32, int hi, ...
;   float psa = 0.f, psb = 0.f; u32x4 wa, wb, wc, wd;
;     ...
; #pragma unroll
;   for (int d0 = 0; d0 < 8; ++d0) { int cb = (d0 * 16 + hi * 8) * 2;
;     bf16x8 b0 = *reinterpret_cast<const bf16x8*>((const char*)Ks + KSWZ(r32, cb));
;     bf16x8 b1 = *reinterpret_cast<const bf16x8*>((const char*)Ks + KSWZ(32 + r32, cb));
;     SBAR(); if (d0 == 0) n0 = __builtin_amdgcn_mfma_f32_32x32x16_bf16(b0, qr[0], negm, 0, 0, 0); else n0 = __builtin_amdgcn_mfma_f32_32x32x16_bf16(b0, qr[d0], n0, 0, 0, 0);
;     SBAR(); QF_CHUNK(2 * d0); SBAR();
;     if (d0 == 0) n1 = __builtin_amdgcn_mfma_f32_32x32x16_bf16(b1, qr[0], negm, 0, 0, 0); else n1 = __builtin_amdgcn_mfma_f32_32x32x16_bf16(b1, qr[d0], n1, 0, 0, 0);
;     SBAR(); QF_CHUNK(2 * d0 + 1); SBAR();
;     if (d0 == 7) { vf8_read<0>(vf0, vbv); SBAR(); } }
;     ...
;   psb += P1[15]; wd[3] = cvtpk(P1[14], P1[15]);
;   l_reg = l_reg * alpha + (psa + psb);
;   pa0 = *reinterpret_cast<bf16x8*>(&wa); pa1 = *reinterpret_cast<bf16x8*>(&wb); pa2 = *reinterpret_cast<bf16x8*>(&wc); pa3 = *reinterpret_cast<bf16x8*>(&wd);
; }
.LBB0_453:
	s_add_i32 s97, s96, 0xffff8000
	s_xor_b32 s98, s96, 0x10000
	s_add_i32 s99, s96, 0x8000
	s_and_b32 s99, s99, 0x18000
	ds_read_b128 v[98:101], v184 offset:49152
	ds_read_b128 v[196:199], v184 offset:57344
	ds_read_b128 v[248:251], v185 offset:49152
	ds_read_b128 v[252:255], v185 offset:57344
	v_add_u32_e32 v0, s97, v235
	s_waitcnt lgkmcnt(3)
	v_mfma_f32_32x32x16_bf16 v[132:147], v[98:101], v[152:155], v[66:81]
	v_exp_f32_e32 v82, v82
	s_waitcnt lgkmcnt(2)
	v_mfma_f32_32x32x16_bf16 v[98:113], v[196:199], v[152:155], v[66:81]
	v_exp_f32_e32 v83, v83
	v_add_f32_e32 v245, v115, v114
	v_cvt_pk_bf16_f32 v196, v114, v115
	ds_read_b128 v[202:205], v186 offset:49152
	ds_read_b128 v[206:209], v186 offset:57344
	s_waitcnt lgkmcnt(3)
	v_mfma_f32_32x32x16_bf16 v[132:147], v[248:251], v[160:163], v[132:147]
	v_exp_f32_e32 v84, v84
	v_add_f32_e32 v245, v116, v245
	v_add_f32_e32 v246, v82, v83
	s_waitcnt lgkmcnt(2)
	v_mfma_f32_32x32x16_bf16 v[98:113], v[252:255], v[160:163], v[98:113]
	v_exp_f32_e32 v85, v85
	v_add_f32_e32 v245, v117, v245
	v_add_f32_e32 v246, v246, v84
	v_cvt_pk_bf16_f32 v197, v116, v117
	v_cvt_pk_bf16_f32 v200, v82, v83
	ds_read_b128 v[248:251], v187 offset:49152
	ds_read_b128 v[252:255], v187 offset:57344
	s_waitcnt lgkmcnt(3)
	v_mfma_f32_32x32x16_bf16 v[132:147], v[202:205], v[148:151], v[132:147]
	v_exp_f32_e32 v86, v86
	v_add_f32_e32 v245, v118, v245
	v_add_f32_e32 v246, v246, v85
	s_waitcnt lgkmcnt(2)
	v_mfma_f32_32x32x16_bf16 v[98:113], v[206:209], v[148:151], v[98:113]
	v_exp_f32_e32 v87, v87
	v_add_f32_e32 v245, v119, v245
	v_add_f32_e32 v246, v246, v86
	v_cvt_pk_bf16_f32 v198, v118, v119
	v_cvt_pk_bf16_f32 v201, v84, v85
	ds_read_b128 v[204:207], v188 offset:49152
	ds_read_b128 v[208:211], v188 offset:57344
	s_waitcnt lgkmcnt(3)
	v_mfma_f32_32x32x16_bf16 v[132:147], v[248:251], v[156:159], v[132:147]
	v_exp_f32_e32 v88, v88
	v_add_f32_e32 v245, v120, v245
	v_add_f32_e32 v246, v246, v87
	s_waitcnt lgkmcnt(2)
	v_mfma_f32_32x32x16_bf16 v[98:113], v[252:255], v[156:159], v[98:113]
	v_exp_f32_e32 v89, v89
	v_add_f32_e32 v245, v121, v245
	v_add_f32_e32 v246, v246, v88
	v_cvt_pk_bf16_f32 v199, v120, v121
	v_cvt_pk_bf16_f32 v202, v86, v87
	ds_read_b128 v[248:251], v189 offset:49152
	ds_read_b128 v[252:255], v189 offset:57344
	s_waitcnt lgkmcnt(3)
	v_mfma_f32_32x32x16_bf16 v[132:147], v[204:207], v[168:171], v[132:147]
	v_exp_f32_e32 v90, v90
	v_add_f32_e32 v245, v122, v245
	v_add_f32_e32 v246, v246, v89
	s_waitcnt lgkmcnt(2)
	v_mfma_f32_32x32x16_bf16 v[98:113], v[208:211], v[168:171], v[98:113]
	v_exp_f32_e32 v91, v91
	v_add_f32_e32 v245, v123, v245
	v_add_f32_e32 v246, v246, v90
	v_cvt_pk_bf16_f32 v204, v122, v123
	v_cvt_pk_bf16_f32 v203, v88, v89
	ds_read_b128 v[114:117], v190 offset:49152
	ds_read_b128 v[118:121], v190 offset:57344
	s_waitcnt lgkmcnt(3)
	v_mfma_f32_32x32x16_bf16 v[132:147], v[248:251], v[176:179], v[132:147]
	v_exp_f32_e32 v92, v92
	v_add_f32_e32 v245, v124, v245
	v_add_f32_e32 v246, v246, v91
	s_waitcnt lgkmcnt(2)
	v_mfma_f32_32x32x16_bf16 v[98:113], v[252:255], v[176:179], v[98:113]
	v_exp_f32_e32 v93, v93
	v_add_f32_e32 v245, v125, v245
	v_add_f32_e32 v246, v246, v92
	v_cvt_pk_bf16_f32 v205, v124, v125
	v_cvt_pk_bf16_f32 v208, v90, v91
	ds_read_b128 v[248:251], v191 offset:49152
	ds_read_b128 v[252:255], v191 offset:57344
	s_waitcnt lgkmcnt(3)
	v_mfma_f32_32x32x16_bf16 v[132:147], v[114:117], v[164:167], v[132:147]
	v_exp_f32_e32 v94, v94
	v_add_f32_e32 v245, v126, v245
	v_add_f32_e32 v246, v246, v93
	s_waitcnt lgkmcnt(2)
	v_mfma_f32_32x32x16_bf16 v[98:113], v[118:121], v[164:167], v[98:113]
	v_exp_f32_e32 v95, v95
	v_add_f32_e32 v245, v127, v245
	v_add_f32_e32 v246, v246, v94
	v_cvt_pk_bf16_f32 v206, v126, v127
	v_cvt_pk_bf16_f32 v209, v92, v93
	s_waitcnt lgkmcnt(1)
	v_mfma_f32_32x32x16_bf16 v[132:147], v[248:251], v[172:175], v[132:147]
	v_exp_f32_e32 v96, v96
	v_add_f32_e32 v245, v128, v245
	v_add_f32_e32 v246, v246, v95
	s_waitcnt lgkmcnt(0)
	v_mfma_f32_32x32x16_bf16 v[98:113], v[252:255], v[172:175], v[98:113]
	v_exp_f32_e32 v97, v97
	v_add_f32_e32 v245, v129, v245
	v_add_f32_e32 v246, v246, v96
	v_cvt_pk_bf16_f32 v207, v128, v129
	v_cvt_pk_bf16_f32 v210, v94, v95
	v_mov_b32_e32 v131, v97
	v_cvt_pk_bf16_f32 v211, v96, v97
	ds_read_b64_tr_b16 v[94:95], v0 offset:0
	ds_read_b64_tr_b16 v[96:97], v0 offset:2048
	ds_read_b64_tr_b16 v[90:91], v0 offset:4096
	ds_read_b64_tr_b16 v[92:93], v0 offset:6144
	ds_read_b64_tr_b16 v[86:87], v0 offset:8192
	ds_read_b64_tr_b16 v[88:89], v0 offset:10240
	ds_read_b64_tr_b16 v[82:83], v0 offset:12288
	ds_read_b64_tr_b16 v[84:85], v0 offset:14336
	s_andn2_b64 s[8:9], exec, s[0:1]
	s_andn2_b64 vcc, exec, s[0:1]
	s_cbranch_vccnz .LBB0_456
	v_max_f32_e32 v114, v132, v133
	v_max3_f32 v114, v114, v134, v135
	v_max3_f32 v114, v114, v136, v137
	v_max3_f32 v114, v114, v138, v139
	v_max3_f32 v114, v114, v140, v141
	v_max3_f32 v114, v114, v142, v143
	v_max3_f32 v114, v114, v144, v145
	v_max3_f32 v114, v114, v146, v147
	v_max3_f32 v114, v114, v98, v99
	v_max3_f32 v114, v114, v100, v101
	v_max3_f32 v114, v114, v102, v103
	v_max3_f32 v114, v114, v104, v105
	v_max3_f32 v114, v114, v106, v107
	v_max3_f32 v114, v114, v108, v109
	v_max3_f32 v114, v114, v110, v111
	v_max3_f32 v114, v114, v112, v113
	v_mov_b32_e32 v115, v114
	s_nop 1
	v_permlane32_swap_b32_e32 v114, v115
	v_max_f32_e32 v114, v114, v115
	v_cmp_ge_f32_e32 vcc, s69, v114
	s_cmp_eq_u64 vcc, exec
	v_mov_b32_e32 v130, 1.0
	s_cbranch_scc1 .LBB0_457
	v_max_f32_e32 v66, v114, v114
	v_max_f32_e32 v66, 0, v66
	v_exp_f32_e64 v130, -v66
	v_add_f32_e32 v222, v222, v66
	v_sub_f32_e32 v147, v147, v66
	v_sub_f32_e32 v146, v146, v66
	v_sub_f32_e32 v145, v145, v66
	v_sub_f32_e32 v144, v144, v66
	v_sub_f32_e32 v143, v143, v66
	v_sub_f32_e32 v142, v142, v66
	v_sub_f32_e32 v141, v141, v66
	v_sub_f32_e32 v140, v140, v66
	v_sub_f32_e32 v139, v139, v66
	v_sub_f32_e32 v138, v138, v66
	v_sub_f32_e32 v137, v137, v66
	v_sub_f32_e32 v136, v136, v66
	v_sub_f32_e32 v135, v135, v66
	v_sub_f32_e32 v134, v134, v66
	v_sub_f32_e32 v133, v133, v66
	v_sub_f32_e32 v132, v132, v66
	v_sub_f32_e32 v113, v113, v66
	v_sub_f32_e32 v112, v112, v66
	v_sub_f32_e32 v111, v111, v66
	v_sub_f32_e32 v110, v110, v66
	v_sub_f32_e32 v109, v109, v66
	v_sub_f32_e32 v108, v108, v66
	v_sub_f32_e32 v107, v107, v66
	v_sub_f32_e32 v106, v106, v66
	v_sub_f32_e32 v105, v105, v66
	v_sub_f32_e32 v104, v104, v66
	v_sub_f32_e32 v103, v103, v66
	v_sub_f32_e32 v102, v102, v66
	v_sub_f32_e32 v101, v101, v66
	v_sub_f32_e32 v100, v100, v66
	v_sub_f32_e32 v99, v99, v66
	v_sub_f32_e32 v98, v98, v66
	v_xor_b32_e32 v66, 0x80000000, v222
	v_mov_b32_e32 v67, v66
	v_mov_b32_e32 v68, v66
	v_mov_b32_e32 v69, v66
	v_mov_b32_e32 v70, v66
	v_mov_b32_e32 v71, v66
	v_mov_b32_e32 v72, v66
	v_mov_b32_e32 v73, v66
	v_mov_b32_e32 v74, v66
	v_mov_b32_e32 v75, v66
	v_mov_b32_e32 v76, v66
	v_mov_b32_e32 v77, v66
	v_mov_b32_e32 v78, v66
	v_mov_b32_e32 v79, v66
	v_mov_b32_e32 v80, v66
	v_mov_b32_e32 v81, v66
	s_branch .LBB0_457

; #define SBAR() __builtin_amdgcn_sched_barrier(0)
; __device__ __forceinline__ unsigned cvtpk(float lo, float hi) { unsigned r; asm volatile("v_cvt_pk_bf16_f32 %0, %1, %2" : "=v"(r) : "v"(lo), "v"(hi)); return r; }
; template <bool FIRST, bool DOEXP = true>
; __device__ __forceinline__ void partialSM(f32x16& p0, f32x16& p1, float& m_reg, f32x16& negm, float& alpha, const bool track = true) {
;     ...
;   float pmax = p0[0];
; #pragma unroll
;   for (int r = 1; r < 16; ++r) pmax = fmaxf(pmax, p0[r]);
; #pragma unroll
;   for (int r = 0; r < 16; ++r) pmax = fmaxf(pmax, p1[r]);
;   { auto rr = __builtin_amdgcn_permlane32_swap(__float_as_uint(pmax), __float_as_uint(pmax), false, false);
;     pmax = fmaxf(__uint_as_float(rr[0]), __uint_as_float(rr[1])); }
;   if (!FIRST && __builtin_expect(__all(pmax <= THRL), 1)) { alpha = 1.f; }
; __device__ __forceinline__ void qkt_fin(f32x16& n0, f32x16& n1, const bf16_t* Ks, const bf16x8* qr, const f32x16& negm, int r32, int hi, ...
;   float psa = 0.f, psb = 0.f; u32x4 wa, wb, wc, wd;
;     ...
; #pragma unroll
;   for (int d0 = 0; d0 < 8; ++d0) { int cb = (d0 * 16 + hi * 8) * 2;
;     bf16x8 b0 = *reinterpret_cast<const bf16x8*>((const char*)Ks + KSWZ(r32, cb));
;     bf16x8 b1 = *reinterpret_cast<const bf16x8*>((const char*)Ks + KSWZ(32 + r32, cb));
;     SBAR(); if (d0 == 0) n0 = __builtin_amdgcn_mfma_f32_32x32x16_bf16(b0, qr[0], negm, 0, 0, 0); else n0 = __builtin_amdgcn_mfma_f32_32x32x16_bf16(b0, qr[d0], n0, 0, 0, 0);
;     SBAR(); QF_CHUNK(2 * d0); SBAR();
;     if (d0 == 0) n1 = __builtin_amdgcn_mfma_f32_32x32x16_bf16(b1, qr[0], negm, 0, 0, 0); else n1 = __builtin_amdgcn_mfma_f32_32x32x16_bf16(b1, qr[d0], n1, 0, 0, 0);
;     SBAR(); QF_CHUNK(2 * d0 + 1); SBAR();
;     if (d0 == 7) { vf8_read<0>(vf0, vbv); SBAR(); } }
;     ...
;   psb += P1[15]; wd[3] = cvtpk(P1[14], P1[15]);
;   l_reg = l_reg * alpha + (psa + psb);
;   pa0 = *reinterpret_cast<bf16x8*>(&wa); pa1 = *reinterpret_cast<bf16x8*>(&wb); pa2 = *reinterpret_cast<bf16x8*>(&wc); pa3 = *reinterpret_cast<bf16x8*>(&wd);
; }
.LBB0_461:
	s_waitcnt lgkmcnt(0)
	v_xor_b32_e32 v184, 0x10000, v184
	ds_read_b128 v[204:207], v184 offset:16384
	ds_read_b128 v[208:211], v184 offset:24576
	v_xor_b32_e32 v185, 0x10000, v185
	ds_read_b128 v[248:251], v185 offset:16384
	ds_read_b128 v[252:255], v185 offset:24576
	v_add_u32_e32 v203, s96, v235
	s_waitcnt lgkmcnt(3)
	v_mfma_f32_32x32x16_bf16 v[114:129], v[204:207], v[152:155], v[66:81]
	v_exp_f32_e32 v98, v98
	s_waitcnt lgkmcnt(2)
	v_mfma_f32_32x32x16_bf16 v[82:97], v[208:211], v[152:155], v[66:81]
	v_exp_f32_e32 v99, v99
	v_add_f32_e32 v201, v133, v132
	v_cvt_pk_bf16_f32 v132, v132, v133
	v_xor_b32_e32 v186, 0x10000, v186
	ds_read_b128 v[204:207], v186 offset:16384
	ds_read_b128 v[208:211], v186 offset:24576
	s_waitcnt lgkmcnt(3)
	v_mfma_f32_32x32x16_bf16 v[114:129], v[248:251], v[160:163], v[114:129]
	v_exp_f32_e32 v100, v100
	v_add_f32_e32 v201, v134, v201
	v_add_f32_e32 v202, v98, v99
	s_waitcnt lgkmcnt(2)
	v_mfma_f32_32x32x16_bf16 v[82:97], v[252:255], v[160:163], v[82:97]
	v_exp_f32_e32 v101, v101
	v_add_f32_e32 v201, v135, v201
	v_add_f32_e32 v202, v202, v100
	v_cvt_pk_bf16_f32 v133, v134, v135
	v_cvt_pk_bf16_f32 v196, v98, v99
	v_xor_b32_e32 v187, 0x10000, v187
	ds_read_b128 v[248:251], v187 offset:16384
	ds_read_b128 v[252:255], v187 offset:24576
	s_waitcnt lgkmcnt(3)
	v_mfma_f32_32x32x16_bf16 v[114:129], v[204:207], v[148:151], v[114:129]
	v_exp_f32_e32 v102, v102
	v_add_f32_e32 v201, v136, v201
	v_add_f32_e32 v202, v202, v101
	s_waitcnt lgkmcnt(2)
	v_mfma_f32_32x32x16_bf16 v[82:97], v[208:211], v[148:151], v[82:97]
	v_exp_f32_e32 v103, v103
	v_add_f32_e32 v201, v137, v201
	v_add_f32_e32 v202, v202, v102
	v_cvt_pk_bf16_f32 v134, v136, v137
	v_cvt_pk_bf16_f32 v197, v100, v101
	v_xor_b32_e32 v188, 0x10000, v188
	ds_read_b128 v[204:207], v188 offset:16384
	ds_read_b128 v[208:211], v188 offset:24576
	s_waitcnt lgkmcnt(3)
	v_mfma_f32_32x32x16_bf16 v[114:129], v[248:251], v[156:159], v[114:129]
	v_exp_f32_e32 v104, v104
	v_add_f32_e32 v201, v138, v201
	v_add_f32_e32 v202, v202, v103
	s_waitcnt lgkmcnt(2)
	v_mfma_f32_32x32x16_bf16 v[82:97], v[252:255], v[156:159], v[82:97]
	v_exp_f32_e32 v105, v105
	v_add_f32_e32 v201, v139, v201
	v_add_f32_e32 v202, v202, v104
	v_cvt_pk_bf16_f32 v135, v138, v139
	v_cvt_pk_bf16_f32 v198, v102, v103
	v_xor_b32_e32 v189, 0x10000, v189
	ds_read_b128 v[248:251], v189 offset:16384
	ds_read_b128 v[252:255], v189 offset:24576
	s_waitcnt lgkmcnt(3)
	v_mfma_f32_32x32x16_bf16 v[114:129], v[204:207], v[168:171], v[114:129]
	v_exp_f32_e32 v106, v106
	v_add_f32_e32 v201, v140, v201
	v_add_f32_e32 v202, v202, v105
	s_waitcnt lgkmcnt(2)
	v_mfma_f32_32x32x16_bf16 v[82:97], v[208:211], v[168:171], v[82:97]
	v_exp_f32_e32 v107, v107
	v_add_f32_e32 v201, v141, v201
	v_add_f32_e32 v202, v202, v106
	v_cvt_pk_bf16_f32 v136, v140, v141
	v_cvt_pk_bf16_f32 v199, v104, v105
	v_xor_b32_e32 v190, 0x10000, v190
	ds_read_b128 v[204:207], v190 offset:16384
	ds_read_b128 v[208:211], v190 offset:24576
	s_waitcnt lgkmcnt(3)
	v_mfma_f32_32x32x16_bf16 v[114:129], v[248:251], v[176:179], v[114:129]
	v_exp_f32_e32 v108, v108
	v_add_f32_e32 v201, v142, v201
	v_add_f32_e32 v202, v202, v107
	s_waitcnt lgkmcnt(2)
	v_mfma_f32_32x32x16_bf16 v[82:97], v[252:255], v[176:179], v[82:97]
	v_exp_f32_e32 v109, v109
	v_add_f32_e32 v201, v143, v201
	v_add_f32_e32 v202, v202, v108
	v_cvt_pk_bf16_f32 v137, v142, v143
	v_cvt_pk_bf16_f32 v140, v106, v107
	v_xor_b32_e32 v191, 0x10000, v191
	ds_read_b128 v[248:251], v191 offset:16384
	ds_read_b128 v[252:255], v191 offset:24576
	s_waitcnt lgkmcnt(3)
	v_mfma_f32_32x32x16_bf16 v[114:129], v[204:207], v[164:167], v[114:129]
	v_exp_f32_e32 v110, v110
	v_add_f32_e32 v201, v144, v201
	v_add_f32_e32 v202, v202, v109
	s_waitcnt lgkmcnt(2)
	v_mfma_f32_32x32x16_bf16 v[82:97], v[208:211], v[164:167], v[82:97]
	v_exp_f32_e32 v111, v111
	v_add_f32_e32 v201, v145, v201
	v_add_f32_e32 v202, v202, v110
	v_cvt_pk_bf16_f32 v138, v144, v145
	v_cvt_pk_bf16_f32 v141, v108, v109
	s_waitcnt lgkmcnt(1)
	v_mfma_f32_32x32x16_bf16 v[114:129], v[248:251], v[172:175], v[114:129]
	v_exp_f32_e32 v112, v112
	v_add_f32_e32 v201, v146, v201
	v_add_f32_e32 v202, v202, v111
	s_waitcnt lgkmcnt(0)
	v_mfma_f32_32x32x16_bf16 v[82:97], v[252:255], v[172:175], v[82:97]
	v_exp_f32_e32 v113, v113
	v_add_f32_e32 v201, v147, v201
	v_add_f32_e32 v202, v202, v112
	v_cvt_pk_bf16_f32 v139, v146, v147
	v_cvt_pk_bf16_f32 v142, v110, v111
	ds_read_b64_tr_b16 v[144:145], v203 offset:0
	ds_read_b64_tr_b16 v[146:147], v203 offset:2048
	s_nop 0
	ds_read_b64_tr_b16 v[106:107], v203 offset:4096
	ds_read_b64_tr_b16 v[108:109], v203 offset:6144
	ds_read_b64_tr_b16 v[102:103], v203 offset:8192
	ds_read_b64_tr_b16 v[104:105], v203 offset:10240
	ds_read_b64_tr_b16 v[98:99], v203 offset:12288
	ds_read_b64_tr_b16 v[100:101], v203 offset:14336
	v_cvt_pk_bf16_f32 v143, v112, v113
	s_and_b64 vcc, exec, s[8:9]
	v_mov_b32_e32 v200, 1.0
	s_cbranch_vccnz .LBB0_463
	v_max_f32_e32 v110, v114, v115
	v_max3_f32 v110, v110, v116, v117
	v_max3_f32 v110, v110, v118, v119
	v_max3_f32 v110, v110, v120, v121
	v_max3_f32 v110, v110, v122, v123
	v_max3_f32 v110, v110, v124, v125
	v_max3_f32 v110, v110, v126, v127
	v_max3_f32 v110, v110, v128, v129
	v_max3_f32 v110, v110, v82, v83
	v_max3_f32 v110, v110, v84, v85
	v_max3_f32 v110, v110, v86, v87
	v_max3_f32 v110, v110, v88, v89
	v_max3_f32 v110, v110, v90, v91
	v_max3_f32 v110, v110, v92, v93
	v_max3_f32 v110, v110, v94, v95
	v_max3_f32 v110, v110, v96, v97
	v_mov_b32_e32 v111, v110
	s_nop 1
	v_permlane32_swap_b32_e32 v110, v111
	v_max_f32_e32 v110, v110, v111
	v_cmp_ge_f32_e32 vcc, s69, v110
	s_cmp_eq_u64 vcc, exec
	v_mov_b32_e32 v200, 1.0
	s_cbranch_scc0 .LBB0_469

; #define SBAR() __builtin_amdgcn_sched_barrier(0)
; __device__ __forceinline__ unsigned cvtpk(float lo, float hi) { unsigned r; asm volatile("v_cvt_pk_bf16_f32 %0, %1, %2" : "=v"(r) : "v"(lo), "v"(hi)); return r; }
; __device__ __forceinline__ void qkt_fin(f32x16& n0, f32x16& n1, const bf16_t* Ks, const bf16x8* qr, const f32x16& negm, int r32, int hi, ...
;   float psa = 0.f, psb = 0.f; u32x4 wa, wb, wc, wd;
;     ...
; #pragma unroll
;   for (int d0 = 0; d0 < 8; ++d0) { int cb = (d0 * 16 + hi * 8) * 2;
;     bf16x8 b0 = *reinterpret_cast<const bf16x8*>((const char*)Ks + KSWZ(r32, cb));
;     bf16x8 b1 = *reinterpret_cast<const bf16x8*>((const char*)Ks + KSWZ(32 + r32, cb));
;     SBAR(); if (d0 == 0) n0 = __builtin_amdgcn_mfma_f32_32x32x16_bf16(b0, qr[0], negm, 0, 0, 0); else n0 = __builtin_amdgcn_mfma_f32_32x32x16_bf16(b0, qr[d0], n0, 0, 0, 0);
;     SBAR(); QF_CHUNK(2 * d0); SBAR();
;     if (d0 == 0) n1 = __builtin_amdgcn_mfma_f32_32x32x16_bf16(b1, qr[0], negm, 0, 0, 0); else n1 = __builtin_amdgcn_mfma_f32_32x32x16_bf16(b1, qr[d0], n1, 0, 0, 0);
;     SBAR(); QF_CHUNK(2 * d0 + 1); SBAR();
;     if (d0 == 7) { vf8_read<0>(vf0, vbv); SBAR(); } }
;     ...
;   psb += P1[15]; wd[3] = cvtpk(P1[14], P1[15]);
;   l_reg = l_reg * alpha + (psa + psb);
;   pa0 = *reinterpret_cast<bf16x8*>(&wa); pa1 = *reinterpret_cast<bf16x8*>(&wb); pa2 = *reinterpret_cast<bf16x8*>(&wc); pa3 = *reinterpret_cast<bf16x8*>(&wd);
; }
.Lh2_453:
	s_setprio 1
	s_add_i32 s97, s96, 0xffff8000
	s_xor_b32 s98, s96, 0x10000
	s_add_i32 s99, s96, 0x8000
	s_and_b32 s99, s99, 0x18000
	ds_read_b128 v[98:101], v184 offset:49152
	ds_read_b128 v[196:199], v184 offset:57344
	ds_read_b128 v[248:251], v185 offset:49152
	ds_read_b128 v[252:255], v185 offset:57344
	v_add_u32_e32 v0, s97, v235
	s_waitcnt lgkmcnt(3)
	v_mfma_f32_32x32x16_bf16 v[132:147], v[98:101], v[152:155], v[66:81]
	v_exp_f32_e32 v82, v82
	s_waitcnt lgkmcnt(2)
	v_mfma_f32_32x32x16_bf16 v[98:113], v[196:199], v[152:155], v[66:81]
	v_exp_f32_e32 v83, v83
	v_add_f32_e32 v245, v115, v114
	v_cvt_pk_bf16_f32 v196, v114, v115
	ds_read_b128 v[202:205], v186 offset:49152
	ds_read_b128 v[206:209], v186 offset:57344
	s_waitcnt lgkmcnt(3)
	v_mfma_f32_32x32x16_bf16 v[132:147], v[248:251], v[160:163], v[132:147]
	v_exp_f32_e32 v84, v84
	v_add_f32_e32 v245, v116, v245
	v_add_f32_e32 v246, v82, v83
	s_waitcnt lgkmcnt(2)
	v_mfma_f32_32x32x16_bf16 v[98:113], v[252:255], v[160:163], v[98:113]
	v_exp_f32_e32 v85, v85
	v_add_f32_e32 v245, v117, v245
	v_add_f32_e32 v246, v246, v84
	v_cvt_pk_bf16_f32 v197, v116, v117
	v_cvt_pk_bf16_f32 v200, v82, v83
	ds_read_b128 v[248:251], v187 offset:49152
	ds_read_b128 v[252:255], v187 offset:57344
	s_add_i32 s79, s99, s100
	s_add_i32 m0, s79, 0x4000
	s_add_i32 s79, s79, 0x6000
	global_load_lds_dwordx4 v180, s[82:83]
	s_waitcnt lgkmcnt(3)
	v_mfma_f32_32x32x16_bf16 v[132:147], v[202:205], v[148:151], v[132:147]
	v_exp_f32_e32 v86, v86
	v_add_f32_e32 v245, v118, v245
	v_add_f32_e32 v246, v246, v85
	s_waitcnt lgkmcnt(2)
	v_mfma_f32_32x32x16_bf16 v[98:113], v[206:209], v[148:151], v[98:113]
	v_exp_f32_e32 v87, v87
	v_add_f32_e32 v245, v119, v245
	v_add_f32_e32 v246, v246, v86
	v_cvt_pk_bf16_f32 v198, v118, v119
	v_cvt_pk_bf16_f32 v201, v84, v85
	ds_read_b128 v[204:207], v188 offset:49152
	ds_read_b128 v[208:211], v188 offset:57344
	s_mov_b32 m0, s79
	s_add_i32 s79, s99, s101
	global_load_lds_dwordx4 v182, s[82:83]
	s_waitcnt lgkmcnt(3)
	v_mfma_f32_32x32x16_bf16 v[132:147], v[248:251], v[156:159], v[132:147]
	v_exp_f32_e32 v88, v88
	v_add_f32_e32 v245, v120, v245
	v_add_f32_e32 v246, v246, v87
	s_waitcnt lgkmcnt(2)
	v_mfma_f32_32x32x16_bf16 v[98:113], v[252:255], v[156:159], v[98:113]
	v_exp_f32_e32 v89, v89
	v_add_f32_e32 v245, v121, v245
	v_add_f32_e32 v246, v246, v88
	v_cvt_pk_bf16_f32 v199, v120, v121
	v_cvt_pk_bf16_f32 v202, v86, v87
	ds_read_b128 v[248:251], v189 offset:49152
	ds_read_b128 v[252:255], v189 offset:57344
	s_mov_b32 m0, s79
	s_add_i32 s79, s79, 0x380
	global_load_lds_dwordx4 v214, s[82:83]
	s_waitcnt lgkmcnt(3)
	v_mfma_f32_32x32x16_bf16 v[132:147], v[204:207], v[168:171], v[132:147]
	v_exp_f32_e32 v90, v90
	v_add_f32_e32 v245, v122, v245
	v_add_f32_e32 v246, v246, v89
	s_waitcnt lgkmcnt(2)
	v_mfma_f32_32x32x16_bf16 v[98:113], v[208:211], v[168:171], v[98:113]
	v_exp_f32_e32 v91, v91
	v_add_f32_e32 v245, v123, v245
	v_add_f32_e32 v246, v246, v90
	v_cvt_pk_bf16_f32 v204, v122, v123
	v_cvt_pk_bf16_f32 v203, v88, v89
	ds_read_b128 v[114:117], v190 offset:49152
	ds_read_b128 v[118:121], v190 offset:57344
	s_mov_b32 m0, s79
	s_nop 0
	global_load_lds_dwordx4 v214, s[82:83] offset:128
	s_add_u32 s82, s82, s76
	s_addc_u32 s83, s83, s77
	s_waitcnt lgkmcnt(3)
	v_mfma_f32_32x32x16_bf16 v[132:147], v[248:251], v[176:179], v[132:147]
	v_exp_f32_e32 v92, v92
	v_add_f32_e32 v245, v124, v245
	v_add_f32_e32 v246, v246, v91
	s_waitcnt lgkmcnt(2)
	v_mfma_f32_32x32x16_bf16 v[98:113], v[252:255], v[176:179], v[98:113]
	v_exp_f32_e32 v93, v93
	v_add_f32_e32 v245, v125, v245
	v_add_f32_e32 v246, v246, v92
	v_cvt_pk_bf16_f32 v205, v124, v125
	v_cvt_pk_bf16_f32 v208, v90, v91
	ds_read_b128 v[248:251], v191 offset:49152
	ds_read_b128 v[252:255], v191 offset:57344
	s_waitcnt lgkmcnt(3)
	v_mfma_f32_32x32x16_bf16 v[132:147], v[114:117], v[164:167], v[132:147]
	v_exp_f32_e32 v94, v94
	v_add_f32_e32 v245, v126, v245
	v_add_f32_e32 v246, v246, v93
	s_waitcnt lgkmcnt(2)
	v_mfma_f32_32x32x16_bf16 v[98:113], v[118:121], v[164:167], v[98:113]
	v_exp_f32_e32 v95, v95
	v_add_f32_e32 v245, v127, v245
	v_add_f32_e32 v246, v246, v94
	v_cvt_pk_bf16_f32 v206, v126, v127
	v_cvt_pk_bf16_f32 v209, v92, v93
	s_waitcnt lgkmcnt(1)
	v_mfma_f32_32x32x16_bf16 v[132:147], v[248:251], v[172:175], v[132:147]
	v_exp_f32_e32 v96, v96
	v_add_f32_e32 v245, v128, v245
	v_add_f32_e32 v246, v246, v95
	s_waitcnt lgkmcnt(0)
	v_mfma_f32_32x32x16_bf16 v[98:113], v[252:255], v[172:175], v[98:113]
	v_exp_f32_e32 v97, v97
	v_add_f32_e32 v245, v129, v245
	v_add_f32_e32 v246, v246, v96
	v_cvt_pk_bf16_f32 v207, v128, v129
	v_cvt_pk_bf16_f32 v210, v94, v95
	v_mov_b32_e32 v131, v97
	v_cvt_pk_bf16_f32 v211, v96, v97
	ds_read_b64_tr_b16 v[94:95], v0 offset:0
	ds_read_b64_tr_b16 v[96:97], v0 offset:2048
	ds_read_b64_tr_b16 v[90:91], v0 offset:4096
	ds_read_b64_tr_b16 v[92:93], v0 offset:6144
	ds_read_b64_tr_b16 v[86:87], v0 offset:8192
	ds_read_b64_tr_b16 v[88:89], v0 offset:10240
	ds_read_b64_tr_b16 v[82:83], v0 offset:12288
	ds_read_b64_tr_b16 v[84:85], v0 offset:14336
	s_andn2_b64 s[8:9], exec, s[0:1]
	s_andn2_b64 vcc, exec, s[0:1]
	s_cbranch_vccnz .Lh2_456
; template <bool FIRST, bool DOEXP = true>
; __device__ __forceinline__ void partialSM(f32x16& p0, f32x16& p1, float& m_reg, f32x16& negm, float& alpha, const bool track = true) {
;     ...
;   float pmax = p0[0];
; #pragma unroll
;   for (int r = 1; r < 16; ++r) pmax = fmaxf(pmax, p0[r]);
; #pragma unroll
;   for (int r = 0; r < 16; ++r) pmax = fmaxf(pmax, p1[r]);
;   { auto rr = __builtin_amdgcn_permlane32_swap(__float_as_uint(pmax), __float_as_uint(pmax), false, false);
;     pmax = fmaxf(__uint_as_float(rr[0]), __uint_as_float(rr[1])); }
;   if (!FIRST && __builtin_expect(__all(pmax <= THRL), 1)) { alpha = 1.f; }
;   else { const float dl = FIRST ? pmax : fmaxf(pmax, 0.f); m_reg += dl; alpha = FIRST ? 1.f : __builtin_amdgcn_exp2f(-dl);
; #pragma unroll
;     for (int r = 0; r < 16; ++r) { p0[r] -= dl; p1[r] -= dl; }
; #pragma unroll
;     for (int r = 0; r < 16; ++r) negm[r] = -m_reg;
;     asm volatile("" : "+v"(negm)); }
	v_max_f32_e32 v114, v132, v133
	v_max3_f32 v114, v114, v134, v135
	v_max3_f32 v114, v114, v136, v137
	v_max3_f32 v114, v114, v138, v139
	v_max3_f32 v114, v114, v140, v141
	v_max3_f32 v114, v114, v142, v143
	v_max3_f32 v114, v114, v144, v145
	v_max3_f32 v114, v114, v146, v147
	v_max3_f32 v114, v114, v98, v99
	v_max3_f32 v114, v114, v100, v101
	v_max3_f32 v114, v114, v102, v103
	v_max3_f32 v114, v114, v104, v105
	v_max3_f32 v114, v114, v106, v107
	v_max3_f32 v114, v114, v108, v109
	v_max3_f32 v114, v114, v110, v111
	v_max3_f32 v114, v114, v112, v113
	v_mov_b32_e32 v115, v114
	s_nop 1
	v_permlane32_swap_b32_e32 v114, v115
	v_max_f32_e32 v114, v114, v115
	v_cmp_ge_f32_e32 vcc, s69, v114
	s_cmp_eq_u64 vcc, exec
	v_mov_b32_e32 v130, 1.0
	s_cbranch_scc1 .Lh2_457
	v_max_f32_e32 v66, v114, v114
	v_max_f32_e32 v66, 0, v66
	v_exp_f32_e64 v130, -v66
	v_add_f32_e32 v222, v222, v66
	v_sub_f32_e32 v147, v147, v66
	v_sub_f32_e32 v146, v146, v66
	v_sub_f32_e32 v145, v145, v66
	v_sub_f32_e32 v144, v144, v66
	v_sub_f32_e32 v143, v143, v66
	v_sub_f32_e32 v142, v142, v66
	v_sub_f32_e32 v141, v141, v66
	v_sub_f32_e32 v140, v140, v66
	v_sub_f32_e32 v139, v139, v66
	v_sub_f32_e32 v138, v138, v66
	v_sub_f32_e32 v137, v137, v66
	v_sub_f32_e32 v136, v136, v66
	v_sub_f32_e32 v135, v135, v66
	v_sub_f32_e32 v134, v134, v66
	v_sub_f32_e32 v133, v133, v66
	v_sub_f32_e32 v132, v132, v66
	v_sub_f32_e32 v113, v113, v66
	v_sub_f32_e32 v112, v112, v66
	v_sub_f32_e32 v111, v111, v66
	v_sub_f32_e32 v110, v110, v66
	v_sub_f32_e32 v109, v109, v66
	v_sub_f32_e32 v108, v108, v66
	v_sub_f32_e32 v107, v107, v66
	v_sub_f32_e32 v106, v106, v66
	v_sub_f32_e32 v105, v105, v66
	v_sub_f32_e32 v104, v104, v66
	v_sub_f32_e32 v103, v103, v66
	v_sub_f32_e32 v102, v102, v66
	v_sub_f32_e32 v101, v101, v66
	v_sub_f32_e32 v100, v100, v66
	v_sub_f32_e32 v99, v99, v66
	v_sub_f32_e32 v98, v98, v66
	v_xor_b32_e32 v66, 0x80000000, v222
	v_mov_b32_e32 v67, v66
	v_mov_b32_e32 v68, v66
	v_mov_b32_e32 v69, v66
	v_mov_b32_e32 v70, v66
	v_mov_b32_e32 v71, v66
	v_mov_b32_e32 v72, v66
	v_mov_b32_e32 v73, v66
	v_mov_b32_e32 v74, v66
	v_mov_b32_e32 v75, v66
	v_mov_b32_e32 v76, v66
	v_mov_b32_e32 v77, v66
	v_mov_b32_e32 v78, v66
	v_mov_b32_e32 v79, v66
	v_mov_b32_e32 v80, v66
	v_mov_b32_e32 v81, v66
	s_branch .Lh2_457

; #define SBAR() __builtin_amdgcn_sched_barrier(0)
; __device__ __forceinline__ unsigned cvtpk(float lo, float hi) { unsigned r; asm volatile("v_cvt_pk_bf16_f32 %0, %1, %2" : "=v"(r) : "v"(lo), "v"(hi)); return r; }
; template <bool FIRST, bool DOEXP = true>
; __device__ __forceinline__ void partialSM(f32x16& p0, f32x16& p1, float& m_reg, f32x16& negm, float& alpha, const bool track = true) {
;     ...
;   float pmax = p0[0];
; #pragma unroll
;   for (int r = 1; r < 16; ++r) pmax = fmaxf(pmax, p0[r]);
; #pragma unroll
;   for (int r = 0; r < 16; ++r) pmax = fmaxf(pmax, p1[r]);
;   { auto rr = __builtin_amdgcn_permlane32_swap(__float_as_uint(pmax), __float_as_uint(pmax), false, false);
;     pmax = fmaxf(__uint_as_float(rr[0]), __uint_as_float(rr[1])); }
;   if (!FIRST && __builtin_expect(__all(pmax <= THRL), 1)) { alpha = 1.f; }
; __device__ __forceinline__ void qkt_fin(f32x16& n0, f32x16& n1, const bf16_t* Ks, const bf16x8* qr, const f32x16& negm, int r32, int hi, ...
;   float psa = 0.f, psb = 0.f; u32x4 wa, wb, wc, wd;
;     ...
; #pragma unroll
;   for (int d0 = 0; d0 < 8; ++d0) { int cb = (d0 * 16 + hi * 8) * 2;
;     bf16x8 b0 = *reinterpret_cast<const bf16x8*>((const char*)Ks + KSWZ(r32, cb));
;     bf16x8 b1 = *reinterpret_cast<const bf16x8*>((const char*)Ks + KSWZ(32 + r32, cb));
;     SBAR(); if (d0 == 0) n0 = __builtin_amdgcn_mfma_f32_32x32x16_bf16(b0, qr[0], negm, 0, 0, 0); else n0 = __builtin_amdgcn_mfma_f32_32x32x16_bf16(b0, qr[d0], n0, 0, 0, 0);
;     SBAR(); QF_CHUNK(2 * d0); SBAR();
;     if (d0 == 0) n1 = __builtin_amdgcn_mfma_f32_32x32x16_bf16(b1, qr[0], negm, 0, 0, 0); else n1 = __builtin_amdgcn_mfma_f32_32x32x16_bf16(b1, qr[d0], n1, 0, 0, 0);
;     SBAR(); QF_CHUNK(2 * d0 + 1); SBAR();
;     if (d0 == 7) { vf8_read<0>(vf0, vbv); SBAR(); } }
;     ...
;   psb += P1[15]; wd[3] = cvtpk(P1[14], P1[15]);
;   l_reg = l_reg * alpha + (psa + psb);
;   pa0 = *reinterpret_cast<bf16x8*>(&wa); pa1 = *reinterpret_cast<bf16x8*>(&wb); pa2 = *reinterpret_cast<bf16x8*>(&wc); pa3 = *reinterpret_cast<bf16x8*>(&wd);
; }
.Lh2_461:
	s_setprio 1
	s_waitcnt lgkmcnt(0)
	s_waitcnt vmcnt(0)
	s_barrier
	v_xor_b32_e32 v184, 0x10000, v184
	ds_read_b128 v[204:207], v184 offset:16384
	ds_read_b128 v[208:211], v184 offset:24576
	v_xor_b32_e32 v185, 0x10000, v185
	ds_read_b128 v[248:251], v185 offset:16384
	ds_read_b128 v[252:255], v185 offset:24576
	v_add_u32_e32 v203, s96, v235
	s_waitcnt lgkmcnt(3)
	v_mfma_f32_32x32x16_bf16 v[114:129], v[204:207], v[152:155], v[66:81]
	v_exp_f32_e32 v98, v98
	s_waitcnt lgkmcnt(2)
	v_mfma_f32_32x32x16_bf16 v[82:97], v[208:211], v[152:155], v[66:81]
	v_exp_f32_e32 v99, v99
	v_add_f32_e32 v201, v133, v132
	v_cvt_pk_bf16_f32 v132, v132, v133
	v_xor_b32_e32 v186, 0x10000, v186
	ds_read_b128 v[204:207], v186 offset:16384
	ds_read_b128 v[208:211], v186 offset:24576
	s_waitcnt lgkmcnt(3)
	v_mfma_f32_32x32x16_bf16 v[114:129], v[248:251], v[160:163], v[114:129]
	v_exp_f32_e32 v100, v100
	v_add_f32_e32 v201, v134, v201
	v_add_f32_e32 v202, v98, v99
	s_waitcnt lgkmcnt(2)
	v_mfma_f32_32x32x16_bf16 v[82:97], v[252:255], v[160:163], v[82:97]
	v_exp_f32_e32 v101, v101
	v_add_f32_e32 v201, v135, v201
	v_add_f32_e32 v202, v202, v100
	v_cvt_pk_bf16_f32 v133, v134, v135
	v_cvt_pk_bf16_f32 v196, v98, v99
	v_xor_b32_e32 v187, 0x10000, v187
	ds_read_b128 v[248:251], v187 offset:16384
	ds_read_b128 v[252:255], v187 offset:24576
	s_add_i32 s79, s98, s100
	s_add_i32 m0, s79, 0x4000
	s_add_i32 s79, s79, 0x6000
	global_load_lds_dwordx4 v180, s[82:83]
	s_waitcnt lgkmcnt(3)
	v_mfma_f32_32x32x16_bf16 v[114:129], v[204:207], v[148:151], v[114:129]
	v_exp_f32_e32 v102, v102
	v_add_f32_e32 v201, v136, v201
	v_add_f32_e32 v202, v202, v101
	s_waitcnt lgkmcnt(2)
	v_mfma_f32_32x32x16_bf16 v[82:97], v[208:211], v[148:151], v[82:97]
	v_exp_f32_e32 v103, v103
	v_add_f32_e32 v201, v137, v201
	v_add_f32_e32 v202, v202, v102
	v_cvt_pk_bf16_f32 v134, v136, v137
	v_cvt_pk_bf16_f32 v197, v100, v101
	v_xor_b32_e32 v188, 0x10000, v188
	ds_read_b128 v[204:207], v188 offset:16384
	ds_read_b128 v[208:211], v188 offset:24576
	s_mov_b32 m0, s79
	s_add_i32 s79, s98, s101
	global_load_lds_dwordx4 v182, s[82:83]
	s_waitcnt lgkmcnt(3)
	v_mfma_f32_32x32x16_bf16 v[114:129], v[248:251], v[156:159], v[114:129]
	v_exp_f32_e32 v104, v104
	v_add_f32_e32 v201, v138, v201
	v_add_f32_e32 v202, v202, v103
	s_waitcnt lgkmcnt(2)
	v_mfma_f32_32x32x16_bf16 v[82:97], v[252:255], v[156:159], v[82:97]
	v_exp_f32_e32 v105, v105
	v_add_f32_e32 v201, v139, v201
	v_add_f32_e32 v202, v202, v104
	v_cvt_pk_bf16_f32 v135, v138, v139
	v_cvt_pk_bf16_f32 v198, v102, v103
	v_xor_b32_e32 v189, 0x10000, v189
	ds_read_b128 v[248:251], v189 offset:16384
	ds_read_b128 v[252:255], v189 offset:24576
	s_mov_b32 m0, s79
	s_add_i32 s79, s79, 0x380
	global_load_lds_dwordx4 v214, s[82:83]
	s_waitcnt lgkmcnt(3)
	v_mfma_f32_32x32x16_bf16 v[114:129], v[204:207], v[168:171], v[114:129]
	v_exp_f32_e32 v106, v106
	v_add_f32_e32 v201, v140, v201
	v_add_f32_e32 v202, v202, v105
	s_waitcnt lgkmcnt(2)
	v_mfma_f32_32x32x16_bf16 v[82:97], v[208:211], v[168:171], v[82:97]
	v_exp_f32_e32 v107, v107
	v_add_f32_e32 v201, v141, v201
	v_add_f32_e32 v202, v202, v106
	v_cvt_pk_bf16_f32 v136, v140, v141
	v_cvt_pk_bf16_f32 v199, v104, v105
	v_xor_b32_e32 v190, 0x10000, v190
	ds_read_b128 v[204:207], v190 offset:16384
	ds_read_b128 v[208:211], v190 offset:24576
	s_mov_b32 m0, s79
	s_nop 0
	global_load_lds_dwordx4 v214, s[82:83] offset:128
	s_add_u32 s82, s82, s76
	s_addc_u32 s83, s83, s77
	s_waitcnt lgkmcnt(3)
	v_mfma_f32_32x32x16_bf16 v[114:129], v[248:251], v[176:179], v[114:129]
	v_exp_f32_e32 v108, v108
	v_add_f32_e32 v201, v142, v201
	v_add_f32_e32 v202, v202, v107
	s_waitcnt lgkmcnt(2)
	v_mfma_f32_32x32x16_bf16 v[82:97], v[252:255], v[176:179], v[82:97]
	v_exp_f32_e32 v109, v109
	v_add_f32_e32 v201, v143, v201
	v_add_f32_e32 v202, v202, v108
	v_cvt_pk_bf16_f32 v137, v142, v143
	v_cvt_pk_bf16_f32 v140, v106, v107
	v_xor_b32_e32 v191, 0x10000, v191
	ds_read_b128 v[248:251], v191 offset:16384
	ds_read_b128 v[252:255], v191 offset:24576
	s_waitcnt lgkmcnt(3)
	v_mfma_f32_32x32x16_bf16 v[114:129], v[204:207], v[164:167], v[114:129]
	v_exp_f32_e32 v110, v110
	v_add_f32_e32 v201, v144, v201
	v_add_f32_e32 v202, v202, v109
	s_waitcnt lgkmcnt(2)
	v_mfma_f32_32x32x16_bf16 v[82:97], v[208:211], v[164:167], v[82:97]
	v_exp_f32_e32 v111, v111
	v_add_f32_e32 v201, v145, v201
	v_add_f32_e32 v202, v202, v110
	v_cvt_pk_bf16_f32 v138, v144, v145
	v_cvt_pk_bf16_f32 v141, v108, v109
	s_waitcnt lgkmcnt(1)
	v_mfma_f32_32x32x16_bf16 v[114:129], v[248:251], v[172:175], v[114:129]
	v_exp_f32_e32 v112, v112
	v_add_f32_e32 v201, v146, v201
	v_add_f32_e32 v202, v202, v111
	s_waitcnt lgkmcnt(0)
	v_mfma_f32_32x32x16_bf16 v[82:97], v[252:255], v[172:175], v[82:97]
	v_exp_f32_e32 v113, v113
	v_add_f32_e32 v201, v147, v201
	v_add_f32_e32 v202, v202, v112
	v_cvt_pk_bf16_f32 v139, v146, v147
	v_cvt_pk_bf16_f32 v142, v110, v111
	ds_read_b64_tr_b16 v[144:145], v203 offset:0
	ds_read_b64_tr_b16 v[146:147], v203 offset:2048
	s_nop 0
	ds_read_b64_tr_b16 v[106:107], v203 offset:4096
	ds_read_b64_tr_b16 v[108:109], v203 offset:6144
	ds_read_b64_tr_b16 v[102:103], v203 offset:8192
	ds_read_b64_tr_b16 v[104:105], v203 offset:10240
	ds_read_b64_tr_b16 v[98:99], v203 offset:12288
	ds_read_b64_tr_b16 v[100:101], v203 offset:14336
	v_cvt_pk_bf16_f32 v143, v112, v113
	s_and_b64 vcc, exec, s[8:9]
	v_mov_b32_e32 v200, 1.0
	s_cbranch_vccnz .Lh2_463
	v_max_f32_e32 v110, v114, v115
	v_max3_f32 v110, v110, v116, v117
	v_max3_f32 v110, v110, v118, v119
	v_max3_f32 v110, v110, v120, v121
	v_max3_f32 v110, v110, v122, v123
	v_max3_f32 v110, v110, v124, v125
	v_max3_f32 v110, v110, v126, v127
	v_max3_f32 v110, v110, v128, v129
	v_max3_f32 v110, v110, v82, v83
	v_max3_f32 v110, v110, v84, v85
	v_max3_f32 v110, v110, v86, v87
	v_max3_f32 v110, v110, v88, v89
	v_max3_f32 v110, v110, v90, v91
	v_max3_f32 v110, v110, v92, v93
	v_max3_f32 v110, v110, v94, v95
	v_max3_f32 v110, v110, v96, v97
	v_mov_b32_e32 v111, v110
	s_nop 1
	v_permlane32_swap_b32_e32 v110, v111
	v_max_f32_e32 v110, v110, v111
	v_cmp_ge_f32_e32 vcc, s69, v110
	s_cmp_eq_u64 vcc, exec
	v_mov_b32_e32 v200, 1.0
	s_cbranch_scc0 .Lh2_469
